# GEMM1 epilogue 16-byte stores marked sc1 (write-through) so the seam release fence finds fewer dirty L2 lines
# baseline (speedup 1.0000x reference)
.LBB0_210:
	v_ashrrev_i32_e32 v98, 6, v118
	v_and_b32_e32 v100, 1, v98
	v_cmp_eq_u32_e32 vcc, 1, v100
	s_movk_i32 s3, 0x2200
	v_mul_lo_u32 v101, v98, s3
	v_cndmask_b32_e32 v100, 0, v125, vcc
	v_add_u32_e32 v108, s6, v100
	v_ashrrev_i32_e32 v100, 1, v118
	v_and_b32_e32 v100, 0xffffffc0, v100
	v_add_u32_e32 v116, s4, v100
	s_movk_i32 s3, 0x3ff
	v_cmp_lt_i32_e64 s[10:11], s3, v116
	v_add_u32_e32 v98, 0xfffff400, v116
	s_movk_i32 s3, 0xf9ff
	v_cmp_lt_u32_e64 s[8:9], s3, v98
	v_subrev_co_u32_e32 v98, vcc, 0xa00, v116
	v_lshrrev_b32_e32 v100, 6, v98
	s_movk_i32 s3, 0x180
	v_mad_u64_u32 v[112:113], s[4:5], v100, s3, 0
	s_movk_i32 s3, 0x800
	v_lshrrev_b32_e32 v100, 3, v118
	v_lshlrev_b32_e32 v102, 2, v118
	v_cmp_gt_u32_e64 s[6:7], s3, v116
	s_mov_b64 s[98:99], s[6:7]
	s_movk_i32 s3, 0x7ff
	v_and_b32_e32 v159, 4, v100
	v_and_b32_e32 v100, 32, v118
	v_and_b32_e32 v155, 60, v102
	v_cmp_lt_u32_e64 s[4:5], s3, v116
	v_lshl_or_b32 v158, v100, 2, v101
	v_lshl_or_b32 v139, v155, 2, v101
	v_cndmask_b32_e64 v101, v128, v129, s[4:5]
	v_add_u32_e32 v102, v101, v116
	v_bfe_u32 v154, v118, 4, 2
	v_lshrrev_b32_e32 v105, 6, v102
	s_movk_i32 s3, 0x6000
	v_and_b32_e32 v161, 31, v118
	v_or_b32_e32 v151, 4, v154
	v_or_b32_e32 v148, 8, v154
	v_or_b32_e32 v146, 12, v154
	v_or_b32_e32 v144, 16, v154
	v_or_b32_e32 v142, 20, v154
	v_or_b32_e32 v138, 24, v154
	v_or_b32_e32 v136, 28, v154
	v_ashrrev_i32_e32 v103, 31, v102
	v_mul_lo_u32 v106, v105, s3
	s_movk_i32 s3, 0x600
	v_mov_b32_e32 v117, v99
	s_xor_b64 s[30:31], vcc, -1
	v_mul_u32_u24_e32 v157, 0x110, v161
	v_mad_u32_u24 v156, v161, s56, v158
	v_lshlrev_b32_e32 v153, 9, v154
	v_mul_u32_u24_e32 v152, 0x110, v154
	v_lshlrev_b32_e32 v150, 9, v151
	v_mad_u32_u24 v149, v154, s56, v126
	v_lshlrev_b32_e32 v147, 9, v148
	v_mad_u32_u24 v141, v154, s56, v127
	v_lshlrev_b32_e32 v145, 9, v146
	v_lshlrev_b32_e32 v143, 9, v144
	v_lshlrev_b32_e32 v140, 9, v142
	v_lshlrev_b32_e32 v137, 9, v138
	v_lshlrev_b32_e32 v135, 9, v136
	v_cndmask_b32_e64 v104, v130, 1.0, s[4:5]
	v_mov_b32_e32 v101, v99
	v_ashrrev_i32_e32 v107, 31, v106
	v_cmp_gt_u32_e32 vcc, s3, v116
	v_lshl_add_u64 v[110:111], v[102:103], 1, s[20:21]
	v_lshl_add_u64 v[114:115], v[116:117], 1, s[96:97]
	v_or_b32_e32 v118, v108, v161
	s_and_saveexec_b64 s[12:13], s[10:11]
	s_xor_b64 s[34:35], exec, s[12:13]
	s_cbranch_execz .LBB0_266
	s_and_saveexec_b64 s[12:13], s[8:9]
	s_xor_b64 s[36:37], exec, s[12:13]
	s_cbranch_execz .LBB0_263
	v_cmp_gt_i32_e64 s[12:13], s57, v108
	s_and_saveexec_b64 s[14:15], s[30:31]
	s_xor_b64 s[38:39], exec, s[14:15]
	s_cbranch_execz .LBB0_231
	v_ashrrev_i32_e32 v120, 6, v108
	v_ashrrev_i32_e32 v121, 31, v120
	v_lshl_add_u64 v[120:121], v[112:113], 0, v[120:121]
	v_lshlrev_b64 v[120:121], 6, v[120:121]
	v_and_b32_e32 v105, 63, v118
	v_lshlrev_b32_e32 v118, 1, v105
	v_mov_b32_e32 v119, v99
	v_or3_b32 v122, v120, v159, 32
	v_mov_b32_e32 v123, v121
	v_lshl_add_u64 v[118:119], s[24:25], 0, v[118:119]
	v_lshlrev_b64 v[122:123], 7, v[122:123]
	v_cvt_pk_bf16_f32 v105, v82, v83
	v_lshl_add_u64 v[122:123], v[118:119], 0, v[122:123]
	v_cvt_pk_bf16_f32 v109, v84, v85
	global_store_short v[122:123], v105, off offset:-4096
	global_store_short_d16_hi v[122:123], v105, off offset:-3968
	v_cvt_pk_bf16_f32 v117, v86, v87
	global_store_short v[122:123], v109, off offset:-3840
	global_store_short_d16_hi v[122:123], v109, off offset:-3712
	v_cvt_pk_bf16_f32 v162, v88, v89
	global_store_short v[122:123], v117, off offset:-3072
	global_store_short_d16_hi v[122:123], v117, off offset:-2944
	v_cvt_pk_bf16_f32 v163, v90, v91
	global_store_short v[122:123], v162, off offset:-2816
	global_store_short_d16_hi v[122:123], v162, off offset:-2688
	v_cvt_pk_bf16_f32 v164, v92, v93
	global_store_short v[122:123], v163, off offset:-2048
	global_store_short_d16_hi v[122:123], v163, off offset:-1920
	v_cvt_pk_bf16_f32 v165, v94, v95
	global_store_short v[122:123], v164, off offset:-1792
	global_store_short_d16_hi v[122:123], v164, off offset:-1664
	v_cvt_pk_bf16_f32 v166, v96, v97
	global_store_short v[122:123], v165, off offset:-1024
	global_store_short_d16_hi v[122:123], v165, off offset:-896
	v_cvt_pk_bf16_f32 v167, v66, v67
	global_store_short v[122:123], v166, off offset:-768
	global_store_short_d16_hi v[122:123], v166, off offset:-640
	v_cvt_pk_bf16_f32 v168, v68, v69
	global_store_short v[122:123], v167, off
	global_store_short_d16_hi v[122:123], v167, off offset:128
	v_cvt_pk_bf16_f32 v169, v70, v71
	global_store_short v[122:123], v168, off offset:256
	global_store_short_d16_hi v[122:123], v168, off offset:384
	v_cvt_pk_bf16_f32 v170, v72, v73
	global_store_short v[122:123], v169, off offset:1024
	global_store_short_d16_hi v[122:123], v169, off offset:1152
	v_cvt_pk_bf16_f32 v171, v74, v75
	global_store_short v[122:123], v170, off offset:1280
	global_store_short_d16_hi v[122:123], v170, off offset:1408
	v_cvt_pk_bf16_f32 v172, v76, v77
	global_store_short v[122:123], v171, off offset:2048
	global_store_short_d16_hi v[122:123], v171, off offset:2176
	v_cvt_pk_bf16_f32 v173, v78, v79
	global_store_short v[122:123], v172, off offset:2304
	global_store_short_d16_hi v[122:123], v172, off offset:2432
	v_cvt_pk_bf16_f32 v174, v80, v81
	global_store_short v[122:123], v173, off offset:3072
	global_store_short_d16_hi v[122:123], v173, off offset:3200
	global_store_short v[122:123], v174, off offset:3328
	global_store_short_d16_hi v[122:123], v174, off offset:3456
	s_and_saveexec_b64 s[40:41], s[12:13]
	s_cbranch_execz .LBB0_230
	v_permlane32_swap_b32_e32 v82, v66
	v_permlane32_swap_b32_e32 v83, v67
	v_permlane32_swap_b32_e32 v84, v68
	v_permlane32_swap_b32_e32 v85, v69
	v_ashrrev_i32_e32 v109, 31, v108
	v_permlane32_swap_b32_e32 v86, v70
	v_permlane32_swap_b32_e32 v87, v71
	v_permlane32_swap_b32_e32 v88, v72
	v_permlane32_swap_b32_e32 v89, v73
	v_permlane32_swap_b32_e32 v90, v74
	v_permlane32_swap_b32_e32 v91, v75
	v_permlane32_swap_b32_e32 v92, v76
	v_permlane32_swap_b32_e32 v93, v77
	v_permlane32_swap_b32_e32 v94, v78
	v_permlane32_swap_b32_e32 v95, v79
	v_permlane32_swap_b32_e32 v96, v80
	v_permlane32_swap_b32_e32 v97, v81
	ds_write_b128 v156, v[82:85]
	ds_write_b128 v156, v[66:69] offset:16
	ds_write_b128 v156, v[86:89] offset:32
	ds_write_b128 v156, v[70:73] offset:48
	ds_write_b128 v156, v[90:93] offset:64
	ds_write_b128 v156, v[74:77] offset:80
	ds_write_b128 v156, v[94:97] offset:96
	ds_write_b128 v156, v[78:81] offset:112
	v_lshlrev_b64 v[66:67], 11, v[108:109]
	v_lshl_add_u64 v[66:67], s[26:27], 0, v[66:67]
	v_lshl_add_u64 v[66:67], v[98:99], 2, v[66:67]
	v_lshlrev_b32_e32 v68, 2, v155
	v_mov_b32_e32 v69, v99
	v_lshl_add_u64 v[66:67], v[66:67], 0, v[68:69]
	v_or_b32_e32 v68, v108, v154
	v_cmp_gt_i32_e64 s[14:15], s57, v68
	s_and_saveexec_b64 s[42:43], s[14:15]
	s_cbranch_execz .LBB0_216
	v_lshlrev_b32_e32 v68, 2, v153
	v_mov_b32_e32 v69, v99
	v_lshl_add_u64 v[72:73], v[66:67], 0, v[68:69]
	v_add_u32_e32 v68, v139, v152
	ds_read_b128 v[68:71], v68
	s_waitcnt lgkmcnt(0)
	global_store_dwordx4 v[72:73], v[68:71], off sc1
.LBB0_216:
	s_or_b64 exec, exec, s[42:43]
	s_nop 0
	v_or_b32_e32 v68, v108, v151
	v_cmp_gt_i32_e64 s[14:15], s57, v68
	s_and_saveexec_b64 s[42:43], s[14:15]
	s_cbranch_execz .LBB0_218
	v_lshlrev_b32_e32 v68, 2, v150
	v_mov_b32_e32 v69, v99
	v_lshl_add_u64 v[72:73], v[66:67], 0, v[68:69]
	v_add_u32_e32 v68, v139, v149
	ds_read_b128 v[68:71], v68
	s_waitcnt lgkmcnt(0)
	global_store_dwordx4 v[72:73], v[68:71], off sc1
.LBB0_218:
	s_or_b64 exec, exec, s[42:43]
	s_nop 0
	v_or_b32_e32 v68, v108, v148
	v_cmp_gt_i32_e64 s[14:15], s57, v68
	s_and_saveexec_b64 s[42:43], s[14:15]
	s_cbranch_execz .LBB0_220
	v_lshlrev_b32_e32 v68, 2, v147
	v_mov_b32_e32 v69, v99
	v_lshl_add_u64 v[72:73], v[66:67], 0, v[68:69]
	v_add_u32_e32 v68, v139, v141
	ds_read_b128 v[68:71], v68
	s_waitcnt lgkmcnt(0)
	global_store_dwordx4 v[72:73], v[68:71], off sc1
.LBB0_220:
	s_or_b64 exec, exec, s[42:43]
	s_nop 0
	v_or_b32_e32 v68, v108, v146
	v_cmp_gt_i32_e64 s[14:15], s57, v68
	s_and_saveexec_b64 s[42:43], s[14:15]
	s_cbranch_execz .LBB0_222
	v_lshlrev_b32_e32 v68, 2, v145
	v_mov_b32_e32 v69, v99
	v_lshl_add_u64 v[72:73], v[66:67], 0, v[68:69]
	v_add_u32_e32 v68, v139, v141
	ds_read_b128 v[68:71], v68 offset:1088
	s_waitcnt lgkmcnt(0)
	global_store_dwordx4 v[72:73], v[68:71], off sc1
.LBB0_222:
	s_or_b64 exec, exec, s[42:43]
	s_nop 0
	v_or_b32_e32 v68, v108, v144
	v_cmp_gt_i32_e64 s[14:15], s57, v68
	s_and_saveexec_b64 s[42:43], s[14:15]
	s_cbranch_execz .LBB0_224
	v_lshlrev_b32_e32 v68, 2, v143
	v_mov_b32_e32 v69, v99
	v_lshl_add_u64 v[72:73], v[66:67], 0, v[68:69]
	v_add_u32_e32 v68, v139, v141
	ds_read_b128 v[68:71], v68 offset:2176
	s_waitcnt lgkmcnt(0)
	global_store_dwordx4 v[72:73], v[68:71], off sc1
.LBB0_224:
	s_or_b64 exec, exec, s[42:43]
	s_nop 0
	v_or_b32_e32 v68, v108, v142
	v_cmp_gt_i32_e64 s[14:15], s57, v68
	s_and_saveexec_b64 s[42:43], s[14:15]
	s_cbranch_execz .LBB0_226
	v_lshlrev_b32_e32 v68, 2, v140
	v_mov_b32_e32 v69, v99
	v_lshl_add_u64 v[72:73], v[66:67], 0, v[68:69]
	v_add_u32_e32 v68, v139, v141
	ds_read_b128 v[68:71], v68 offset:3264
	s_waitcnt lgkmcnt(0)
	global_store_dwordx4 v[72:73], v[68:71], off sc1
.LBB0_226:
	s_or_b64 exec, exec, s[42:43]
	s_nop 0
	v_or_b32_e32 v68, v108, v138
	v_cmp_gt_i32_e64 s[14:15], s57, v68
	s_and_saveexec_b64 s[42:43], s[14:15]
	s_cbranch_execz .LBB0_228
	v_lshlrev_b32_e32 v68, 2, v137
	v_mov_b32_e32 v69, v99
	v_lshl_add_u64 v[72:73], v[66:67], 0, v[68:69]
	v_add_u32_e32 v68, v139, v141
	ds_read_b128 v[68:71], v68 offset:4352
	s_waitcnt lgkmcnt(0)
	global_store_dwordx4 v[72:73], v[68:71], off sc1
.LBB0_228:
	s_or_b64 exec, exec, s[42:43]
	s_nop 0
	v_or_b32_e32 v68, v108, v136
	v_cmp_gt_i32_e64 s[14:15], s57, v68
	s_and_b64 exec, exec, s[14:15]
	s_cbranch_execz .LBB0_230
	v_add_u32_e32 v68, v139, v141
	ds_read_b128 v[68:71], v68 offset:5440
	v_lshlrev_b32_e32 v72, 2, v135
	v_mov_b32_e32 v73, v99
	v_lshl_add_u64 v[66:67], v[66:67], 0, v[72:73]
	s_waitcnt lgkmcnt(0)
	global_store_dwordx4 v[66:67], v[68:71], off sc1

.LBB0_244:
	s_or_b64 exec, exec, s[14:15]
	v_pk_mul_f32 v[70:71], v[104:105], v[70:71]
	v_pk_mul_f32 v[72:73], v[104:105], v[72:73]
	v_pk_mul_f32 v[66:67], v[104:105], v[66:67]
	v_cvt_pk_bf16_f32 v70, v70, v71
	v_cvt_pk_bf16_f32 v71, v72, v73
	v_cvt_pk_bf16_f32 v72, v66, v67
	v_pk_mul_f32 v[66:67], v[104:105], v[68:69]
	s_and_b64 s[12:13], s[4:5], s[12:13]
	v_cvt_pk_bf16_f32 v73, v66, v67
	ds_write_b128 v202, v[70:73] offset:48
	ds_read_b128 v[176:179], v204
	ds_read_b128 v[180:183], v204 offset:144
	ds_read_b128 v[184:187], v204 offset:288
	ds_read_b128 v[188:191], v204 offset:432
	s_cmp_lg_u64 s[98:99], 0
	s_cbranch_scc0 .Lg1co_k0
	v_lshl_add_u64 v[192:193], v[122:123], 0, v[206:207]
	s_waitcnt lgkmcnt(3)
	global_store_dwordx4 v[192:193], v[176:179], off sc1
	s_waitcnt lgkmcnt(2)
	global_store_dwordx4 v[192:193], v[180:183], off offset:1024 sc1
	s_waitcnt lgkmcnt(1)
	global_store_dwordx4 v[192:193], v[184:187], off offset:2048 sc1
	s_waitcnt lgkmcnt(0)
	global_store_dwordx4 v[192:193], v[188:191], off offset:3072 sc1
	s_branch .Lg1co_e0
.Lg1co_k0:
	v_lshl_add_u64 v[192:193], v[122:123], 0, v[208:209]
	s_waitcnt lgkmcnt(3)
	global_store_dwordx4 v[192:193], v[176:179], off sc1
	s_waitcnt lgkmcnt(2)
	global_store_dwordx4 v[192:193], v[180:183], off offset:128 sc1
	s_waitcnt lgkmcnt(1)
	global_store_dwordx4 v[192:193], v[184:187], off offset:256 sc1
	s_waitcnt lgkmcnt(0)
	global_store_dwordx4 v[192:193], v[188:191], off offset:384 sc1
.Lg1co_e0:
	s_and_saveexec_b64 s[14:15], s[12:13]
	s_cbranch_execz .LBB0_261
	v_ashrrev_i32_e32 v109, 31, v108
	v_lshlrev_b64 v[66:67], 11, v[108:109]
	v_lshl_add_u64 v[66:67], s[28:29], 0, v[66:67]
	v_lshl_add_u64 v[66:67], v[102:103], 2, v[66:67]
	v_lshlrev_b32_e32 v68, 2, v155
	v_mov_b32_e32 v69, v99
	v_lshl_add_u64 v[66:67], v[66:67], 0, v[68:69]
	v_or_b32_e32 v68, v108, v154
	v_cmp_gt_i32_e64 s[12:13], s57, v68
	s_and_saveexec_b64 s[40:41], s[12:13]
	s_cbranch_execz .LBB0_247
	v_add_u32_e32 v68, v139, v152
	ds_read_b128 v[68:71], v68
	v_lshlrev_b32_e32 v72, 2, v153
	v_mov_b32_e32 v73, v99
	v_lshl_add_u64 v[72:73], v[66:67], 0, v[72:73]
	s_waitcnt lgkmcnt(0)
	global_store_dwordx4 v[72:73], v[68:71], off sc1
.LBB0_247:
	s_or_b64 exec, exec, s[40:41]
	s_nop 0
	v_or_b32_e32 v68, v108, v151
	v_cmp_gt_i32_e64 s[12:13], s57, v68
	s_and_saveexec_b64 s[40:41], s[12:13]
	s_cbranch_execz .LBB0_249
	v_add_u32_e32 v68, v139, v149
	ds_read_b128 v[68:71], v68
	v_lshlrev_b32_e32 v72, 2, v150
	v_mov_b32_e32 v73, v99
	v_lshl_add_u64 v[72:73], v[66:67], 0, v[72:73]
	s_waitcnt lgkmcnt(0)
	global_store_dwordx4 v[72:73], v[68:71], off sc1
.LBB0_249:
	s_or_b64 exec, exec, s[40:41]
	s_nop 0
	v_or_b32_e32 v68, v108, v148
	v_cmp_gt_i32_e64 s[12:13], s57, v68
	s_and_saveexec_b64 s[40:41], s[12:13]
	s_cbranch_execz .LBB0_251
	v_add_u32_e32 v68, v139, v141
	ds_read_b128 v[68:71], v68
	v_lshlrev_b32_e32 v72, 2, v147
	v_mov_b32_e32 v73, v99
	v_lshl_add_u64 v[72:73], v[66:67], 0, v[72:73]
	s_waitcnt lgkmcnt(0)
	global_store_dwordx4 v[72:73], v[68:71], off sc1
.LBB0_251:
	s_or_b64 exec, exec, s[40:41]
	s_nop 0
	v_or_b32_e32 v68, v108, v146
	v_cmp_gt_i32_e64 s[12:13], s57, v68
	s_and_saveexec_b64 s[40:41], s[12:13]
	s_cbranch_execz .LBB0_253
	v_add_u32_e32 v68, v139, v141
	ds_read_b128 v[68:71], v68 offset:1088
	v_lshlrev_b32_e32 v72, 2, v145
	v_mov_b32_e32 v73, v99
	v_lshl_add_u64 v[72:73], v[66:67], 0, v[72:73]
	s_waitcnt lgkmcnt(0)
	global_store_dwordx4 v[72:73], v[68:71], off sc1
.LBB0_253:
	s_or_b64 exec, exec, s[40:41]
	s_nop 0
	v_or_b32_e32 v68, v108, v144
	v_cmp_gt_i32_e64 s[12:13], s57, v68
	s_and_saveexec_b64 s[40:41], s[12:13]
	s_cbranch_execz .LBB0_255
	v_add_u32_e32 v68, v139, v141
	ds_read_b128 v[68:71], v68 offset:2176
	v_lshlrev_b32_e32 v72, 2, v143
	v_mov_b32_e32 v73, v99
	v_lshl_add_u64 v[72:73], v[66:67], 0, v[72:73]
	s_waitcnt lgkmcnt(0)
	global_store_dwordx4 v[72:73], v[68:71], off sc1
.LBB0_255:
	s_or_b64 exec, exec, s[40:41]
	s_nop 0
	v_or_b32_e32 v68, v108, v142
	v_cmp_gt_i32_e64 s[12:13], s57, v68
	s_and_saveexec_b64 s[40:41], s[12:13]
	s_cbranch_execz .LBB0_257
	v_add_u32_e32 v68, v139, v141
	ds_read_b128 v[68:71], v68 offset:3264
	v_lshlrev_b32_e32 v72, 2, v140
	v_mov_b32_e32 v73, v99
	v_lshl_add_u64 v[72:73], v[66:67], 0, v[72:73]
	s_waitcnt lgkmcnt(0)
	global_store_dwordx4 v[72:73], v[68:71], off sc1
.LBB0_257:
	s_or_b64 exec, exec, s[40:41]
	s_nop 0
	v_or_b32_e32 v68, v108, v138
	v_cmp_gt_i32_e64 s[12:13], s57, v68
	s_and_saveexec_b64 s[40:41], s[12:13]
	s_cbranch_execz .LBB0_259
	v_add_u32_e32 v68, v139, v141
	ds_read_b128 v[68:71], v68 offset:4352
	v_lshlrev_b32_e32 v72, 2, v137
	v_mov_b32_e32 v73, v99
	v_lshl_add_u64 v[72:73], v[66:67], 0, v[72:73]
	s_waitcnt lgkmcnt(0)
	global_store_dwordx4 v[72:73], v[68:71], off sc1
.LBB0_259:
	s_or_b64 exec, exec, s[40:41]
	s_nop 0
	v_or_b32_e32 v68, v108, v136
	v_cmp_gt_i32_e64 s[12:13], s57, v68
	s_and_b64 exec, exec, s[12:13]
	s_cbranch_execz .LBB0_261
	v_add_u32_e32 v68, v139, v141
	ds_read_b128 v[68:71], v68 offset:5440
	v_lshlrev_b32_e32 v72, 2, v135
	v_mov_b32_e32 v73, v99
	v_lshl_add_u64 v[66:67], v[66:67], 0, v[72:73]
	s_waitcnt lgkmcnt(0)
	global_store_dwordx4 v[66:67], v[68:71], off sc1

.LBB0_263:
	s_andn2_saveexec_b64 s[12:13], s[36:37]
	s_cbranch_execz .LBB0_265
	v_mul_f32_e32 v105, 0xbfb8aa3b, v82
	v_mul_f32_e32 v109, 0xbfb8aa3b, v66
	v_mul_f32_e32 v117, 0xbfb8aa3b, v83
	v_exp_f32_e32 v105, v105
	v_exp_f32_e32 v109, v109
	v_exp_f32_e32 v117, v117
	v_ashrrev_i32_e32 v119, 31, v118
	v_add_f32_e32 v105, 1.0, v105
	v_add_f32_e32 v109, 1.0, v109
	v_add_f32_e32 v117, 1.0, v117
	v_rcp_f32_e32 v105, v105
	v_rcp_f32_e32 v109, v109
	v_rcp_f32_e32 v117, v117
	v_lshlrev_b64 v[118:119], 10, v[118:119]
	v_lshl_add_u64 v[118:119], v[114:115], 0, v[118:119]
	v_cndmask_b32_e32 v120, v133, v134, vcc
	v_mov_b32_e32 v121, v99
	v_lshl_add_u64 v[118:119], v[118:119], 0, v[120:121]
	v_mul_f32_e32 v120, 0xbfb8aa3b, v67
	v_mul_f32_e32 v82, v82, v105
	v_mul_f32_e32 v105, v66, v109
	v_mul_f32_e32 v83, v83, v117
	v_mul_f32_e32 v109, 0xbfb8aa3b, v84
	v_mul_f32_e32 v117, 0xbfb8aa3b, v68
	v_exp_f32_e32 v120, v120
	v_exp_f32_e32 v109, v109
	v_exp_f32_e32 v117, v117
	v_permlane32_swap_b32_e32 v82, v105
	v_add_f32_e32 v66, 1.0, v120
	v_add_f32_e32 v109, 1.0, v109
	v_add_f32_e32 v117, 1.0, v117
	v_rcp_f32_e32 v66, v66
	v_rcp_f32_e32 v109, v109
	v_rcp_f32_e32 v117, v117
	v_mul_f32_e32 v120, 0xbfb8aa3b, v85
	v_mul_f32_e32 v121, v67, v66
	v_mul_f32_e32 v84, v84, v109
	v_mul_f32_e32 v109, v68, v117
	v_mul_f32_e32 v67, 0xbfb8aa3b, v69
	v_mul_f32_e32 v68, 0xbfb8aa3b, v86
	v_exp_f32_e32 v67, v67
	v_exp_f32_e32 v68, v68
	v_exp_f32_e32 v120, v120
	v_mul_f32_e32 v117, 0xbfb8aa3b, v70
	v_add_f32_e32 v67, 1.0, v67
	v_add_f32_e32 v68, 1.0, v68
	v_rcp_f32_e32 v67, v67
	v_rcp_f32_e32 v68, v68
	v_add_f32_e32 v66, 1.0, v120
	v_rcp_f32_e32 v66, v66
	v_mul_f32_e32 v69, v69, v67
	v_mul_f32_e32 v86, v86, v68
	v_mul_f32_e32 v67, 0xbfb8aa3b, v87
	v_mul_f32_e32 v68, 0xbfb8aa3b, v71
	v_exp_f32_e32 v67, v67
	v_exp_f32_e32 v68, v68
	v_exp_f32_e32 v117, v117
	v_mul_f32_e32 v85, v85, v66
	v_add_f32_e32 v67, 1.0, v67
	v_add_f32_e32 v68, 1.0, v68
	v_rcp_f32_e32 v67, v67
	v_rcp_f32_e32 v68, v68
	v_add_f32_e32 v66, 1.0, v117
	v_mul_f32_e32 v117, 0xbfb8aa3b, v88
	v_mul_f32_e32 v87, v87, v67
	v_mul_f32_e32 v122, v71, v68
	v_mul_f32_e32 v67, 0xbfb8aa3b, v72
	v_mul_f32_e32 v68, 0xbfb8aa3b, v89
	v_exp_f32_e32 v67, v67
	v_exp_f32_e32 v68, v68
	v_rcp_f32_e32 v66, v66
	v_exp_f32_e32 v117, v117
	v_add_f32_e32 v67, 1.0, v67
	v_add_f32_e32 v68, 1.0, v68
	v_rcp_f32_e32 v67, v67
	v_rcp_f32_e32 v68, v68
	v_mul_f32_e32 v120, v70, v66
	v_add_f32_e32 v66, 1.0, v117
	v_mul_f32_e32 v72, v72, v67
	v_mul_f32_e32 v89, v89, v68
	v_mul_f32_e32 v67, 0xbfb8aa3b, v90
	v_mul_f32_e32 v68, 0xbfb8aa3b, v74
	v_exp_f32_e32 v67, v67
	v_exp_f32_e32 v68, v68
	v_mul_f32_e32 v70, 0xbfb8aa3b, v73
	v_rcp_f32_e32 v66, v66
	v_add_f32_e32 v67, 1.0, v67
	v_add_f32_e32 v68, 1.0, v68
	v_rcp_f32_e32 v67, v67
	v_rcp_f32_e32 v68, v68
	v_exp_f32_e32 v70, v70
	v_mul_f32_e32 v88, v88, v66
	v_mul_f32_e32 v90, v90, v67
	v_mul_f32_e32 v74, v74, v68
	v_mul_f32_e32 v67, 0xbfb8aa3b, v75
	v_mul_f32_e32 v68, 0xbfb8aa3b, v92
	v_exp_f32_e32 v67, v67
	v_exp_f32_e32 v68, v68
	v_add_f32_e32 v66, 1.0, v70
	v_mul_f32_e32 v70, 0xbfb8aa3b, v91
	v_add_f32_e32 v67, 1.0, v67
	v_add_f32_e32 v68, 1.0, v68
	v_rcp_f32_e32 v67, v67
	v_rcp_f32_e32 v68, v68
	v_rcp_f32_e32 v66, v66
	v_exp_f32_e32 v70, v70
	v_mul_f32_e32 v75, v75, v67
	v_mul_f32_e32 v92, v92, v68
	v_mul_f32_e32 v67, 0xbfb8aa3b, v93
	v_mul_f32_e32 v68, 0xbfb8aa3b, v77
	v_exp_f32_e32 v67, v67
	v_exp_f32_e32 v68, v68
	v_mul_f32_e32 v73, v73, v66
	v_add_f32_e32 v66, 1.0, v70
	v_mul_f32_e32 v70, 0xbfb8aa3b, v76
	v_add_f32_e32 v67, 1.0, v67
	v_add_f32_e32 v68, 1.0, v68
	v_rcp_f32_e32 v66, v66
	v_exp_f32_e32 v70, v70
	v_rcp_f32_e32 v67, v67
	v_rcp_f32_e32 v68, v68
	v_mul_f32_e32 v91, v91, v66
	v_add_f32_e32 v66, 1.0, v70
	v_mul_f32_e32 v70, 0xbfb8aa3b, v94
	v_mul_f32_e32 v93, v93, v67
	v_mul_f32_e32 v77, v77, v68
	v_mul_f32_e32 v67, 0xbfb8aa3b, v78
	v_mul_f32_e32 v68, 0xbfb8aa3b, v95
	v_rcp_f32_e32 v66, v66
	v_exp_f32_e32 v70, v70
	v_exp_f32_e32 v67, v67
	v_exp_f32_e32 v68, v68
	v_mul_f32_e32 v76, v76, v66
	v_add_f32_e32 v66, 1.0, v70
	v_add_f32_e32 v67, 1.0, v67
	v_add_f32_e32 v68, 1.0, v68
	v_mul_f32_e32 v70, 0xbfb8aa3b, v79
	v_rcp_f32_e32 v66, v66
	v_rcp_f32_e32 v67, v67
	v_rcp_f32_e32 v68, v68
	v_exp_f32_e32 v70, v70
	v_mul_f32_e32 v94, v94, v66
	v_mul_f32_e32 v78, v78, v67
	v_mul_f32_e32 v95, v95, v68
	v_add_f32_e32 v66, 1.0, v70
	v_mul_f32_e32 v67, 0xbfb8aa3b, v96
	v_mul_f32_e32 v68, 0xbfb8aa3b, v80
	v_rcp_f32_e32 v66, v66
	v_exp_f32_e32 v67, v67
	v_exp_f32_e32 v68, v68
	v_mul_f32_e32 v70, 0xbfb8aa3b, v81
	v_mul_f32_e32 v79, v79, v66
	v_add_f32_e32 v66, 1.0, v67
	v_add_f32_e32 v67, 1.0, v68
	v_mul_f32_e32 v68, 0xbfb8aa3b, v97
	v_exp_f32_e32 v68, v68
	v_exp_f32_e32 v70, v70
	v_rcp_f32_e32 v66, v66
	v_rcp_f32_e32 v67, v67
	v_add_f32_e32 v68, 1.0, v68
	v_add_f32_e32 v70, 1.0, v70
	v_rcp_f32_e32 v68, v68
	v_rcp_f32_e32 v70, v70
	v_mul_f32_e32 v96, v96, v66
	v_mul_f32_e32 v80, v80, v67
	v_permlane32_swap_b32_e32 v83, v121
	v_permlane32_swap_b32_e32 v84, v109
	v_permlane32_swap_b32_e32 v85, v69
	v_lshlrev_b32_e32 v66, 1, v100
	v_mov_b32_e32 v67, v99
	v_mul_f32_e32 v97, v97, v68
	v_mul_f32_e32 v81, v81, v70
	v_permlane32_swap_b32_e32 v86, v120
	v_permlane32_swap_b32_e32 v87, v122
	v_permlane32_swap_b32_e32 v88, v72
	v_permlane32_swap_b32_e32 v89, v73
	v_lshl_add_u64 v[70:71], v[118:119], 0, v[66:67]
	v_cvt_pk_bf16_f32 v66, v82, v83
	v_cvt_pk_bf16_f32 v67, v84, v85
	v_cvt_pk_bf16_f32 v68, v105, v121
	v_cvt_pk_bf16_f32 v69, v109, v69
	v_permlane32_swap_b32_e32 v90, v74
	v_permlane32_swap_b32_e32 v91, v75
	v_permlane32_swap_b32_e32 v92, v76
	v_permlane32_swap_b32_e32 v93, v77
	ds_write_b128 v202, v[66:69]
	v_permlane32_swap_b32_e32 v94, v78
	s_nop 0
	v_cvt_pk_bf16_f32 v66, v86, v87
	v_cvt_pk_bf16_f32 v67, v88, v89
	v_cvt_pk_bf16_f32 v68, v120, v122
	v_cvt_pk_bf16_f32 v69, v72, v73
	v_permlane32_swap_b32_e32 v95, v79
	v_permlane32_swap_b32_e32 v96, v80
	v_permlane32_swap_b32_e32 v97, v81
	ds_write_b128 v202, v[66:69] offset:16
	s_nop 1
	v_cvt_pk_bf16_f32 v66, v90, v91
	v_cvt_pk_bf16_f32 v67, v92, v93
	v_cvt_pk_bf16_f32 v68, v74, v75
	v_cvt_pk_bf16_f32 v69, v76, v77
	ds_write_b128 v202, v[66:69] offset:32
	s_nop 1
	v_cvt_pk_bf16_f32 v66, v94, v95
	v_cvt_pk_bf16_f32 v67, v96, v97
	v_cvt_pk_bf16_f32 v68, v78, v79
	v_cvt_pk_bf16_f32 v69, v80, v81
	ds_write_b128 v202, v[66:69] offset:48
	v_lshl_add_u64 v[192:193], v[70:71], 0, v[206:207]
	ds_read_b128 v[176:179], v204
	ds_read_b128 v[180:183], v204 offset:144
	ds_read_b128 v[184:187], v204 offset:288
	ds_read_b128 v[188:191], v204 offset:432
	s_waitcnt lgkmcnt(3)
	global_store_dwordx4 v[192:193], v[176:179], off sc1
	s_waitcnt lgkmcnt(2)
	global_store_dwordx4 v[192:193], v[180:183], off offset:1024 sc1
	s_waitcnt lgkmcnt(1)
	global_store_dwordx4 v[192:193], v[184:187], off offset:2048 sc1
	s_waitcnt lgkmcnt(0)
	global_store_dwordx4 v[192:193], v[188:191], off offset:3072 sc1

.LBB0_266:
	s_or_saveexec_b64 s[14:15], s[34:35]
	v_ashrrev_i32_e32 v116, 1, v116
	v_ashrrev_i32_e32 v117, 31, v116
	v_lshl_add_u64 v[116:117], v[116:117], 1, s[18:19]
	v_lshl_add_u64 v[116:117], v[116:117], 0, v[100:101]
	s_xor_b64 exec, exec, s[14:15]
	s_cbranch_execz .LBB0_268
	v_mul_f32_e32 v66, 0xbfb8aa3b, v66
	v_mul_f32_e32 v67, 0xbfb8aa3b, v67
	v_exp_f32_e32 v66, v66
	v_exp_f32_e32 v67, v67
	v_mul_f32_e32 v68, 0xbfb8aa3b, v68
	v_exp_f32_e32 v68, v68
	v_add_f32_e32 v66, 1.0, v66
	v_add_f32_e32 v67, 1.0, v67
	v_rcp_f32_e32 v66, v66
	v_rcp_f32_e32 v67, v67
	v_cmp_gt_i32_e64 s[12:13], s57, v118
	v_mul_f32_e32 v82, v82, v66
	v_mul_f32_e32 v83, v83, v67
	v_add_f32_e32 v66, 1.0, v68
	v_mul_f32_e32 v67, 0xbfb8aa3b, v69
	v_mul_f32_e32 v68, 0xbfb8aa3b, v70
	v_exp_f32_e32 v67, v67
	v_exp_f32_e32 v68, v68
	v_mul_f32_e32 v69, 0xbfb8aa3b, v71
	v_rcp_f32_e32 v66, v66
	v_add_f32_e32 v67, 1.0, v67
	v_add_f32_e32 v68, 1.0, v68
	v_rcp_f32_e32 v67, v67
	v_rcp_f32_e32 v68, v68
	v_exp_f32_e32 v69, v69
	v_mul_f32_e32 v84, v84, v66
	v_mul_f32_e32 v85, v85, v67
	v_mul_f32_e32 v86, v86, v68
	v_mul_f32_e32 v67, 0xbfb8aa3b, v72
	v_mul_f32_e32 v68, 0xbfb8aa3b, v73
	v_exp_f32_e32 v67, v67
	v_exp_f32_e32 v68, v68
	v_add_f32_e32 v66, 1.0, v69
	v_mul_f32_e32 v69, 0xbfb8aa3b, v74
	v_add_f32_e32 v67, 1.0, v67
	v_add_f32_e32 v68, 1.0, v68
	v_rcp_f32_e32 v67, v67
	v_rcp_f32_e32 v68, v68
	v_rcp_f32_e32 v66, v66
	v_exp_f32_e32 v69, v69
	v_mul_f32_e32 v73, v88, v67
	v_mul_f32_e32 v74, v89, v68
	v_mul_f32_e32 v67, 0xbfb8aa3b, v75
	v_mul_f32_e32 v68, 0xbfb8aa3b, v76
	v_exp_f32_e32 v67, v67
	v_exp_f32_e32 v68, v68
	v_mul_f32_e32 v72, v87, v66
	v_add_f32_e32 v66, 1.0, v69
	v_add_f32_e32 v67, 1.0, v67
	v_add_f32_e32 v68, 1.0, v68
	v_mul_f32_e32 v69, 0xbfb8aa3b, v77
	v_rcp_f32_e32 v66, v66
	v_rcp_f32_e32 v67, v67
	v_rcp_f32_e32 v68, v68
	v_exp_f32_e32 v69, v69
	v_mul_f32_e32 v75, v90, v66
	v_mul_f32_e32 v76, v91, v67
	v_mul_f32_e32 v77, v92, v68
	v_add_f32_e32 v66, 1.0, v69
	v_mul_f32_e32 v67, 0xbfb8aa3b, v78
	v_mul_f32_e32 v68, 0xbfb8aa3b, v79
	v_rcp_f32_e32 v66, v66
	v_exp_f32_e32 v67, v67
	v_exp_f32_e32 v68, v68
	v_mul_f32_e32 v70, 0xbfb8aa3b, v81
	v_mul_f32_e32 v69, v93, v66
	v_add_f32_e32 v66, 1.0, v67
	v_add_f32_e32 v67, 1.0, v68
	v_rcp_f32_e32 v67, v67
	v_mul_f32_e32 v68, 0xbfb8aa3b, v80
	v_rcp_f32_e32 v66, v66
	v_exp_f32_e32 v68, v68
	v_exp_f32_e32 v70, v70
	v_mul_f32_e32 v79, v95, v67
	v_add_u32_e32 v67, 0xffffe000, v108
	v_lshrrev_b32_e32 v67, 12, v67
	v_add_f32_e32 v68, 1.0, v68
	v_add_f32_e32 v70, 1.0, v70
	v_mul_f32_e32 v78, v94, v66
	v_ashrrev_i32_e32 v66, 8, v108
	v_add_u32_e32 v67, 32, v67
	v_rcp_f32_e32 v68, v68
	v_rcp_f32_e32 v70, v70
	v_cndmask_b32_e64 v66, v67, v66, s[12:13]
	v_lshlrev_b32_e32 v66, 5, v66
	v_add3_u32 v66, v118, v66, 16
	v_ashrrev_i32_e32 v67, 31, v66
	v_mul_f32_e32 v80, v96, v68
	v_mul_f32_e32 v81, v97, v70
	v_permlane32_swap_b32_e32 v82, v75
	v_permlane32_swap_b32_e32 v83, v76
	v_permlane32_swap_b32_e32 v84, v77
	v_permlane32_swap_b32_e32 v85, v69
	v_lshlrev_b64 v[66:67], 10, v[66:67]
	v_permlane32_swap_b32_e32 v86, v78
	v_permlane32_swap_b32_e32 v72, v79
	v_permlane32_swap_b32_e32 v73, v80
	v_permlane32_swap_b32_e32 v74, v81
	v_lshl_add_u64 v[70:71], v[116:117], 0, v[66:67]
	v_cvt_pk_bf16_f32 v66, v82, v83
	v_cvt_pk_bf16_f32 v67, v84, v85
	v_cvt_pk_bf16_f32 v68, v75, v76
	v_cvt_pk_bf16_f32 v69, v77, v69
	ds_write_b128 v203, v[66:69]
	s_nop 1
	v_cvt_pk_bf16_f32 v66, v86, v72
	v_cvt_pk_bf16_f32 v67, v73, v74
	v_cvt_pk_bf16_f32 v68, v78, v79
	v_cvt_pk_bf16_f32 v69, v80, v81
	ds_write_b128 v203, v[66:69] offset:16
	v_lshl_add_u64 v[192:193], v[70:71], 0, v[210:211]
	ds_read_b128 v[176:179], v205
	ds_read_b128 v[180:183], v205 offset:144
	s_waitcnt lgkmcnt(1)
	global_store_dwordx4 v[192:193], v[176:179], off sc1
	s_waitcnt lgkmcnt(0)
	global_store_dwordx4 v[192:193], v[180:183], off offset:1024 sc1
.LBB0_268:
	s_or_b64 exec, exec, s[14:15]
	s_nop 0
	v_add_u32_e32 v66, 32, v108
	v_or_b32_e32 v68, v66, v161
	s_and_saveexec_b64 s[12:13], s[10:11]
	s_xor_b64 s[34:35], exec, s[12:13]
	s_cbranch_execz .LBB0_324
	s_and_saveexec_b64 s[12:13], s[8:9]
	s_xor_b64 s[36:37], exec, s[12:13]
	s_cbranch_execz .LBB0_321
	v_cmp_gt_i32_e64 s[12:13], s59, v108
	s_and_saveexec_b64 s[14:15], s[30:31]
	s_xor_b64 s[38:39], exec, s[14:15]
	s_cbranch_execz .LBB0_289
	v_ashrrev_i32_e32 v70, 6, v66
	v_ashrrev_i32_e32 v71, 31, v70
	v_lshl_add_u64 v[70:71], v[112:113], 0, v[70:71]
	v_lshlrev_b64 v[70:71], 6, v[70:71]
	v_and_b32_e32 v67, 63, v68
	v_lshlrev_b32_e32 v68, 1, v67
	v_mov_b32_e32 v69, v99
	v_or3_b32 v72, v70, v159, 32
	v_mov_b32_e32 v73, v71
	v_lshl_add_u64 v[68:69], s[24:25], 0, v[68:69]
	v_lshlrev_b64 v[72:73], 7, v[72:73]
	v_cvt_pk_bf16_f32 v67, v50, v51
	v_lshl_add_u64 v[72:73], v[68:69], 0, v[72:73]
	v_cvt_pk_bf16_f32 v74, v52, v53
	global_store_short v[72:73], v67, off offset:-4096
	global_store_short_d16_hi v[72:73], v67, off offset:-3968
	v_cvt_pk_bf16_f32 v75, v54, v55
	global_store_short v[72:73], v74, off offset:-3840
	global_store_short_d16_hi v[72:73], v74, off offset:-3712
	v_cvt_pk_bf16_f32 v76, v56, v57
	global_store_short v[72:73], v75, off offset:-3072
	global_store_short_d16_hi v[72:73], v75, off offset:-2944
	v_cvt_pk_bf16_f32 v77, v58, v59
	global_store_short v[72:73], v76, off offset:-2816
	global_store_short_d16_hi v[72:73], v76, off offset:-2688
	v_cvt_pk_bf16_f32 v78, v60, v61
	global_store_short v[72:73], v77, off offset:-2048
	global_store_short_d16_hi v[72:73], v77, off offset:-1920
	v_cvt_pk_bf16_f32 v79, v62, v63
	global_store_short v[72:73], v78, off offset:-1792
	global_store_short_d16_hi v[72:73], v78, off offset:-1664
	v_cvt_pk_bf16_f32 v80, v64, v65
	global_store_short v[72:73], v79, off offset:-1024
	global_store_short_d16_hi v[72:73], v79, off offset:-896
	v_cvt_pk_bf16_f32 v81, v34, v35
	global_store_short v[72:73], v80, off offset:-768
	global_store_short_d16_hi v[72:73], v80, off offset:-640
	v_cvt_pk_bf16_f32 v82, v36, v37
	global_store_short v[72:73], v81, off
	global_store_short_d16_hi v[72:73], v81, off offset:128
	v_cvt_pk_bf16_f32 v83, v38, v39
	global_store_short v[72:73], v82, off offset:256
	global_store_short_d16_hi v[72:73], v82, off offset:384
	v_cvt_pk_bf16_f32 v84, v40, v41
	global_store_short v[72:73], v83, off offset:1024
	global_store_short_d16_hi v[72:73], v83, off offset:1152
	v_cvt_pk_bf16_f32 v85, v42, v43
	global_store_short v[72:73], v84, off offset:1280
	global_store_short_d16_hi v[72:73], v84, off offset:1408
	v_cvt_pk_bf16_f32 v86, v44, v45
	global_store_short v[72:73], v85, off offset:2048
	global_store_short_d16_hi v[72:73], v85, off offset:2176
	v_cvt_pk_bf16_f32 v87, v46, v47
	global_store_short v[72:73], v86, off offset:2304
	global_store_short_d16_hi v[72:73], v86, off offset:2432
	v_cvt_pk_bf16_f32 v88, v48, v49
	global_store_short v[72:73], v87, off offset:3072
	global_store_short_d16_hi v[72:73], v87, off offset:3200
	global_store_short v[72:73], v88, off offset:3328
	global_store_short_d16_hi v[72:73], v88, off offset:3456
	s_and_saveexec_b64 s[40:41], s[12:13]
	s_cbranch_execz .LBB0_288
	v_permlane32_swap_b32_e32 v50, v34
	v_permlane32_swap_b32_e32 v51, v35
	v_permlane32_swap_b32_e32 v52, v36
	v_permlane32_swap_b32_e32 v53, v37
	v_ashrrev_i32_e32 v67, 31, v66
	v_permlane32_swap_b32_e32 v54, v38
	v_permlane32_swap_b32_e32 v55, v39
	v_permlane32_swap_b32_e32 v56, v40
	v_permlane32_swap_b32_e32 v57, v41
	v_permlane32_swap_b32_e32 v58, v42
	v_permlane32_swap_b32_e32 v59, v43
	v_permlane32_swap_b32_e32 v60, v44
	v_permlane32_swap_b32_e32 v61, v45
	v_permlane32_swap_b32_e32 v62, v46
	v_permlane32_swap_b32_e32 v63, v47
	v_permlane32_swap_b32_e32 v64, v48
	v_permlane32_swap_b32_e32 v65, v49
	ds_write_b128 v156, v[50:53]
	ds_write_b128 v156, v[34:37] offset:16
	ds_write_b128 v156, v[54:57] offset:32
	ds_write_b128 v156, v[38:41] offset:48
	ds_write_b128 v156, v[58:61] offset:64
	ds_write_b128 v156, v[42:45] offset:80
	ds_write_b128 v156, v[62:65] offset:96
	ds_write_b128 v156, v[46:49] offset:112
	v_lshlrev_b64 v[34:35], 11, v[66:67]
	v_lshl_add_u64 v[34:35], s[26:27], 0, v[34:35]
	v_lshl_add_u64 v[34:35], v[98:99], 2, v[34:35]
	v_lshlrev_b32_e32 v36, 2, v155
	v_mov_b32_e32 v37, v99
	v_lshl_add_u64 v[34:35], v[34:35], 0, v[36:37]
	v_or_b32_e32 v36, v66, v154
	v_cmp_gt_i32_e64 s[14:15], s57, v36
	s_and_saveexec_b64 s[42:43], s[14:15]
	s_cbranch_execz .LBB0_274
	v_lshlrev_b32_e32 v36, 2, v153
	v_mov_b32_e32 v37, v99
	v_lshl_add_u64 v[40:41], v[34:35], 0, v[36:37]
	v_add_u32_e32 v36, v139, v152
	ds_read_b128 v[36:39], v36
	s_waitcnt lgkmcnt(0)
	global_store_dwordx4 v[40:41], v[36:39], off sc1
.LBB0_274:
	s_or_b64 exec, exec, s[42:43]
	s_nop 0
	v_or_b32_e32 v36, v66, v151
	v_cmp_gt_i32_e64 s[14:15], s57, v36
	s_and_saveexec_b64 s[42:43], s[14:15]
	s_cbranch_execz .LBB0_276
	v_lshlrev_b32_e32 v36, 2, v150
	v_mov_b32_e32 v37, v99
	v_lshl_add_u64 v[40:41], v[34:35], 0, v[36:37]
	v_add_u32_e32 v36, v139, v149
	ds_read_b128 v[36:39], v36
	s_waitcnt lgkmcnt(0)
	global_store_dwordx4 v[40:41], v[36:39], off sc1
.LBB0_276:
	s_or_b64 exec, exec, s[42:43]
	s_nop 0
	v_or_b32_e32 v36, v66, v148
	v_cmp_gt_i32_e64 s[14:15], s57, v36
	s_and_saveexec_b64 s[42:43], s[14:15]
	s_cbranch_execz .LBB0_278
	v_lshlrev_b32_e32 v36, 2, v147
	v_mov_b32_e32 v37, v99
	v_lshl_add_u64 v[40:41], v[34:35], 0, v[36:37]
	v_add_u32_e32 v36, v139, v141
	ds_read_b128 v[36:39], v36
	s_waitcnt lgkmcnt(0)
	global_store_dwordx4 v[40:41], v[36:39], off sc1
.LBB0_278:
	s_or_b64 exec, exec, s[42:43]
	s_nop 0
	v_or_b32_e32 v36, v66, v146
	v_cmp_gt_i32_e64 s[14:15], s57, v36
	s_and_saveexec_b64 s[42:43], s[14:15]
	s_cbranch_execz .LBB0_280
	v_lshlrev_b32_e32 v36, 2, v145
	v_mov_b32_e32 v37, v99
	v_lshl_add_u64 v[40:41], v[34:35], 0, v[36:37]
	v_add_u32_e32 v36, v139, v141
	ds_read_b128 v[36:39], v36 offset:1088
	s_waitcnt lgkmcnt(0)
	global_store_dwordx4 v[40:41], v[36:39], off sc1
.LBB0_280:
	s_or_b64 exec, exec, s[42:43]
	s_nop 0
	v_or_b32_e32 v36, v66, v144
	v_cmp_gt_i32_e64 s[14:15], s57, v36
	s_and_saveexec_b64 s[42:43], s[14:15]
	s_cbranch_execz .LBB0_282
	v_lshlrev_b32_e32 v36, 2, v143
	v_mov_b32_e32 v37, v99
	v_lshl_add_u64 v[40:41], v[34:35], 0, v[36:37]
	v_add_u32_e32 v36, v139, v141
	ds_read_b128 v[36:39], v36 offset:2176
	s_waitcnt lgkmcnt(0)
	global_store_dwordx4 v[40:41], v[36:39], off sc1
.LBB0_282:
	s_or_b64 exec, exec, s[42:43]
	s_nop 0
	v_or_b32_e32 v36, v66, v142
	v_cmp_gt_i32_e64 s[14:15], s57, v36
	s_and_saveexec_b64 s[42:43], s[14:15]
	s_cbranch_execz .LBB0_284
	v_lshlrev_b32_e32 v36, 2, v140
	v_mov_b32_e32 v37, v99
	v_lshl_add_u64 v[40:41], v[34:35], 0, v[36:37]
	v_add_u32_e32 v36, v139, v141
	ds_read_b128 v[36:39], v36 offset:3264
	s_waitcnt lgkmcnt(0)
	global_store_dwordx4 v[40:41], v[36:39], off sc1
.LBB0_284:
	s_or_b64 exec, exec, s[42:43]
	s_nop 0
	v_or_b32_e32 v36, v66, v138
	v_cmp_gt_i32_e64 s[14:15], s57, v36
	s_and_saveexec_b64 s[42:43], s[14:15]
	s_cbranch_execz .LBB0_286
	v_lshlrev_b32_e32 v36, 2, v137
	v_mov_b32_e32 v37, v99
	v_lshl_add_u64 v[40:41], v[34:35], 0, v[36:37]
	v_add_u32_e32 v36, v139, v141
	ds_read_b128 v[36:39], v36 offset:4352
	s_waitcnt lgkmcnt(0)
	global_store_dwordx4 v[40:41], v[36:39], off sc1
.LBB0_286:
	s_or_b64 exec, exec, s[42:43]
	s_nop 0
	v_or_b32_e32 v36, v66, v136
	v_cmp_gt_i32_e64 s[14:15], s57, v36
	s_and_b64 exec, exec, s[14:15]
	s_cbranch_execz .LBB0_288
	v_add_u32_e32 v36, v139, v141
	ds_read_b128 v[36:39], v36 offset:5440
	v_lshlrev_b32_e32 v40, 2, v135
	v_mov_b32_e32 v41, v99
	v_lshl_add_u64 v[34:35], v[34:35], 0, v[40:41]
	s_waitcnt lgkmcnt(0)
	global_store_dwordx4 v[34:35], v[36:39], off sc1

.LBB0_302:
	s_or_b64 exec, exec, s[14:15]
	v_pk_mul_f32 v[38:39], v[104:105], v[38:39]
	v_pk_mul_f32 v[40:41], v[104:105], v[40:41]
	v_pk_mul_f32 v[34:35], v[104:105], v[34:35]
	v_cvt_pk_bf16_f32 v38, v38, v39
	v_cvt_pk_bf16_f32 v39, v40, v41
	v_cvt_pk_bf16_f32 v40, v34, v35
	v_pk_mul_f32 v[34:35], v[104:105], v[36:37]
	s_and_b64 s[12:13], s[4:5], s[12:13]
	v_cvt_pk_bf16_f32 v41, v34, v35
	ds_write_b128 v202, v[38:41] offset:48
	ds_read_b128 v[176:179], v204
	ds_read_b128 v[180:183], v204 offset:144
	ds_read_b128 v[184:187], v204 offset:288
	ds_read_b128 v[188:191], v204 offset:432
	s_cmp_lg_u64 s[98:99], 0
	s_cbranch_scc0 .Lg1co_k3
	v_lshl_add_u64 v[192:193], v[72:73], 0, v[206:207]
	s_waitcnt lgkmcnt(3)
	global_store_dwordx4 v[192:193], v[176:179], off sc1
	s_waitcnt lgkmcnt(2)
	global_store_dwordx4 v[192:193], v[180:183], off offset:1024 sc1
	s_waitcnt lgkmcnt(1)
	global_store_dwordx4 v[192:193], v[184:187], off offset:2048 sc1
	s_waitcnt lgkmcnt(0)
	global_store_dwordx4 v[192:193], v[188:191], off offset:3072 sc1
	s_branch .Lg1co_e3
.Lg1co_k3:
	v_lshl_add_u64 v[192:193], v[72:73], 0, v[208:209]
	s_waitcnt lgkmcnt(3)
	global_store_dwordx4 v[192:193], v[176:179], off sc1
	s_waitcnt lgkmcnt(2)
	global_store_dwordx4 v[192:193], v[180:183], off offset:128 sc1
	s_waitcnt lgkmcnt(1)
	global_store_dwordx4 v[192:193], v[184:187], off offset:256 sc1
	s_waitcnt lgkmcnt(0)
	global_store_dwordx4 v[192:193], v[188:191], off offset:384 sc1
.Lg1co_e3:
	s_and_saveexec_b64 s[14:15], s[12:13]
	s_cbranch_execz .LBB0_319
	v_ashrrev_i32_e32 v67, 31, v66
	v_lshlrev_b64 v[34:35], 11, v[66:67]
	v_lshl_add_u64 v[34:35], s[28:29], 0, v[34:35]
	v_lshl_add_u64 v[34:35], v[102:103], 2, v[34:35]
	v_lshlrev_b32_e32 v36, 2, v155
	v_mov_b32_e32 v37, v99
	v_lshl_add_u64 v[34:35], v[34:35], 0, v[36:37]
	v_or_b32_e32 v36, v66, v154
	v_cmp_gt_i32_e64 s[12:13], s57, v36
	s_and_saveexec_b64 s[40:41], s[12:13]
	s_cbranch_execz .LBB0_305
	v_add_u32_e32 v36, v139, v152
	ds_read_b128 v[36:39], v36
	v_lshlrev_b32_e32 v40, 2, v153
	v_mov_b32_e32 v41, v99
	v_lshl_add_u64 v[40:41], v[34:35], 0, v[40:41]
	s_waitcnt lgkmcnt(0)
	global_store_dwordx4 v[40:41], v[36:39], off sc1
.LBB0_305:
	s_or_b64 exec, exec, s[40:41]
	s_nop 0
	v_or_b32_e32 v36, v66, v151
	v_cmp_gt_i32_e64 s[12:13], s57, v36
	s_and_saveexec_b64 s[40:41], s[12:13]
	s_cbranch_execz .LBB0_307
	v_add_u32_e32 v36, v139, v149
	ds_read_b128 v[36:39], v36
	v_lshlrev_b32_e32 v40, 2, v150
	v_mov_b32_e32 v41, v99
	v_lshl_add_u64 v[40:41], v[34:35], 0, v[40:41]
	s_waitcnt lgkmcnt(0)
	global_store_dwordx4 v[40:41], v[36:39], off sc1
.LBB0_307:
	s_or_b64 exec, exec, s[40:41]
	s_nop 0
	v_or_b32_e32 v36, v66, v148
	v_cmp_gt_i32_e64 s[12:13], s57, v36
	s_and_saveexec_b64 s[40:41], s[12:13]
	s_cbranch_execz .LBB0_309
	v_add_u32_e32 v36, v139, v141
	ds_read_b128 v[36:39], v36
	v_lshlrev_b32_e32 v40, 2, v147
	v_mov_b32_e32 v41, v99
	v_lshl_add_u64 v[40:41], v[34:35], 0, v[40:41]
	s_waitcnt lgkmcnt(0)
	global_store_dwordx4 v[40:41], v[36:39], off sc1
.LBB0_309:
	s_or_b64 exec, exec, s[40:41]
	s_nop 0
	v_or_b32_e32 v36, v66, v146
	v_cmp_gt_i32_e64 s[12:13], s57, v36
	s_and_saveexec_b64 s[40:41], s[12:13]
	s_cbranch_execz .LBB0_311
	v_add_u32_e32 v36, v139, v141
	ds_read_b128 v[36:39], v36 offset:1088
	v_lshlrev_b32_e32 v40, 2, v145
	v_mov_b32_e32 v41, v99
	v_lshl_add_u64 v[40:41], v[34:35], 0, v[40:41]
	s_waitcnt lgkmcnt(0)
	global_store_dwordx4 v[40:41], v[36:39], off sc1
.LBB0_311:
	s_or_b64 exec, exec, s[40:41]
	s_nop 0
	v_or_b32_e32 v36, v66, v144
	v_cmp_gt_i32_e64 s[12:13], s57, v36
	s_and_saveexec_b64 s[40:41], s[12:13]
	s_cbranch_execz .LBB0_313
	v_add_u32_e32 v36, v139, v141
	ds_read_b128 v[36:39], v36 offset:2176
	v_lshlrev_b32_e32 v40, 2, v143
	v_mov_b32_e32 v41, v99
	v_lshl_add_u64 v[40:41], v[34:35], 0, v[40:41]
	s_waitcnt lgkmcnt(0)
	global_store_dwordx4 v[40:41], v[36:39], off sc1
.LBB0_313:
	s_or_b64 exec, exec, s[40:41]
	s_nop 0
	v_or_b32_e32 v36, v66, v142
	v_cmp_gt_i32_e64 s[12:13], s57, v36
	s_and_saveexec_b64 s[40:41], s[12:13]
	s_cbranch_execz .LBB0_315
	v_add_u32_e32 v36, v139, v141
	ds_read_b128 v[36:39], v36 offset:3264
	v_lshlrev_b32_e32 v40, 2, v140
	v_mov_b32_e32 v41, v99
	v_lshl_add_u64 v[40:41], v[34:35], 0, v[40:41]
	s_waitcnt lgkmcnt(0)
	global_store_dwordx4 v[40:41], v[36:39], off sc1
.LBB0_315:
	s_or_b64 exec, exec, s[40:41]
	s_nop 0
	v_or_b32_e32 v36, v66, v138
	v_cmp_gt_i32_e64 s[12:13], s57, v36
	s_and_saveexec_b64 s[40:41], s[12:13]
	s_cbranch_execz .LBB0_317
	v_add_u32_e32 v36, v139, v141
	ds_read_b128 v[36:39], v36 offset:4352
	v_lshlrev_b32_e32 v40, 2, v137
	v_mov_b32_e32 v41, v99
	v_lshl_add_u64 v[40:41], v[34:35], 0, v[40:41]
	s_waitcnt lgkmcnt(0)
	global_store_dwordx4 v[40:41], v[36:39], off sc1
.LBB0_317:
	s_or_b64 exec, exec, s[40:41]
	s_nop 0
	v_or_b32_e32 v36, v66, v136
	v_cmp_gt_i32_e64 s[12:13], s57, v36
	s_and_b64 exec, exec, s[12:13]
	s_cbranch_execz .LBB0_319
	v_add_u32_e32 v36, v139, v141
	ds_read_b128 v[36:39], v36 offset:5440
	v_lshlrev_b32_e32 v40, 2, v135
	v_mov_b32_e32 v41, v99
	v_lshl_add_u64 v[34:35], v[34:35], 0, v[40:41]
	s_waitcnt lgkmcnt(0)
	global_store_dwordx4 v[34:35], v[36:39], off sc1

.LBB0_321:
	s_andn2_saveexec_b64 s[12:13], s[36:37]
	s_cbranch_execz .LBB0_323
	v_ashrrev_i32_e32 v69, 31, v68
	v_lshlrev_b64 v[66:67], 10, v[68:69]
	v_mul_f32_e32 v68, 0xbfb8aa3b, v50
	v_exp_f32_e32 v70, v68
	v_lshl_add_u64 v[66:67], v[114:115], 0, v[66:67]
	v_cndmask_b32_e32 v68, v133, v134, vcc
	v_mov_b32_e32 v69, v99
	v_lshl_add_u64 v[66:67], v[66:67], 0, v[68:69]
	v_add_f32_e32 v68, 1.0, v70
	v_mul_f32_e32 v69, 0xbfb8aa3b, v34
	v_mul_f32_e32 v70, 0xbfb8aa3b, v51
	v_exp_f32_e32 v69, v69
	v_exp_f32_e32 v70, v70
	v_rcp_f32_e32 v68, v68
	v_mul_f32_e32 v71, 0xbfb8aa3b, v35
	v_add_f32_e32 v69, 1.0, v69
	v_add_f32_e32 v70, 1.0, v70
	v_rcp_f32_e32 v69, v69
	v_rcp_f32_e32 v70, v70
	v_mul_f32_e32 v50, v50, v68
	v_exp_f32_e32 v71, v71
	v_mul_f32_e32 v68, v34, v69
	v_mul_f32_e32 v51, v51, v70
	v_mul_f32_e32 v69, 0xbfb8aa3b, v52
	v_mul_f32_e32 v70, 0xbfb8aa3b, v36
	v_exp_f32_e32 v69, v69
	v_exp_f32_e32 v70, v70
	v_add_f32_e32 v34, 1.0, v71
	v_rcp_f32_e32 v34, v34
	v_add_f32_e32 v69, 1.0, v69
	v_add_f32_e32 v70, 1.0, v70
	v_rcp_f32_e32 v69, v69
	v_rcp_f32_e32 v70, v70
	v_mul_f32_e32 v72, v35, v34
	v_mul_f32_e32 v35, 0xbfb8aa3b, v37
	v_mul_f32_e32 v52, v52, v69
	v_mul_f32_e32 v69, v36, v70
	v_mul_f32_e32 v36, 0xbfb8aa3b, v54
	v_exp_f32_e32 v35, v35
	v_exp_f32_e32 v36, v36
	v_mul_f32_e32 v71, 0xbfb8aa3b, v53
	v_exp_f32_e32 v71, v71
	v_add_f32_e32 v35, 1.0, v35
	v_add_f32_e32 v36, 1.0, v36
	v_rcp_f32_e32 v35, v35
	v_rcp_f32_e32 v36, v36
	v_add_f32_e32 v34, 1.0, v71
	v_mul_f32_e32 v70, 0xbfb8aa3b, v38
	v_mul_f32_e32 v37, v37, v35
	v_mul_f32_e32 v54, v54, v36
	v_mul_f32_e32 v35, 0xbfb8aa3b, v55
	v_mul_f32_e32 v36, 0xbfb8aa3b, v39
	v_exp_f32_e32 v35, v35
	v_exp_f32_e32 v36, v36
	v_rcp_f32_e32 v34, v34
	v_exp_f32_e32 v70, v70
	v_add_f32_e32 v35, 1.0, v35
	v_add_f32_e32 v36, 1.0, v36
	v_rcp_f32_e32 v35, v35
	v_rcp_f32_e32 v36, v36
	v_mul_f32_e32 v53, v53, v34
	v_add_f32_e32 v34, 1.0, v70
	v_mul_f32_e32 v55, v55, v35
	v_mul_f32_e32 v73, v39, v36
	v_mul_f32_e32 v35, 0xbfb8aa3b, v40
	v_mul_f32_e32 v36, 0xbfb8aa3b, v57
	v_exp_f32_e32 v35, v35
	v_exp_f32_e32 v36, v36
	v_mul_f32_e32 v70, 0xbfb8aa3b, v56
	v_rcp_f32_e32 v34, v34
	v_add_f32_e32 v35, 1.0, v35
	v_add_f32_e32 v36, 1.0, v36
	v_rcp_f32_e32 v35, v35
	v_rcp_f32_e32 v36, v36
	v_exp_f32_e32 v70, v70
	v_mul_f32_e32 v71, v38, v34
	v_mul_f32_e32 v40, v40, v35
	v_mul_f32_e32 v57, v57, v36
	v_mul_f32_e32 v35, 0xbfb8aa3b, v58
	v_mul_f32_e32 v36, 0xbfb8aa3b, v42
	v_exp_f32_e32 v35, v35
	v_exp_f32_e32 v36, v36
	v_add_f32_e32 v34, 1.0, v70
	v_mul_f32_e32 v38, 0xbfb8aa3b, v41
	v_add_f32_e32 v35, 1.0, v35
	v_add_f32_e32 v36, 1.0, v36
	v_rcp_f32_e32 v35, v35
	v_rcp_f32_e32 v36, v36
	v_rcp_f32_e32 v34, v34
	v_exp_f32_e32 v38, v38
	v_mul_f32_e32 v58, v58, v35
	v_mul_f32_e32 v42, v42, v36
	v_mul_f32_e32 v35, 0xbfb8aa3b, v43
	v_mul_f32_e32 v36, 0xbfb8aa3b, v60
	v_exp_f32_e32 v35, v35
	v_exp_f32_e32 v36, v36
	v_mul_f32_e32 v56, v56, v34
	v_add_f32_e32 v34, 1.0, v38
	v_add_f32_e32 v35, 1.0, v35
	v_add_f32_e32 v36, 1.0, v36
	v_rcp_f32_e32 v35, v35
	v_rcp_f32_e32 v36, v36
	v_mul_f32_e32 v38, 0xbfb8aa3b, v59
	v_rcp_f32_e32 v34, v34
	v_mul_f32_e32 v43, v43, v35
	v_mul_f32_e32 v60, v60, v36
	v_mul_f32_e32 v35, 0xbfb8aa3b, v61
	v_mul_f32_e32 v36, 0xbfb8aa3b, v45
	v_exp_f32_e32 v38, v38
	v_exp_f32_e32 v35, v35
	v_exp_f32_e32 v36, v36
	v_mul_f32_e32 v41, v41, v34
	v_add_f32_e32 v34, 1.0, v38
	v_mul_f32_e32 v38, 0xbfb8aa3b, v44
	v_add_f32_e32 v35, 1.0, v35
	v_add_f32_e32 v36, 1.0, v36
	v_rcp_f32_e32 v34, v34
	v_exp_f32_e32 v38, v38
	v_rcp_f32_e32 v35, v35
	v_rcp_f32_e32 v36, v36
	v_mul_f32_e32 v59, v59, v34
	v_add_f32_e32 v34, 1.0, v38
	v_mul_f32_e32 v38, 0xbfb8aa3b, v62
	v_mul_f32_e32 v61, v61, v35
	v_mul_f32_e32 v45, v45, v36
	v_mul_f32_e32 v35, 0xbfb8aa3b, v46
	v_mul_f32_e32 v36, 0xbfb8aa3b, v63
	v_rcp_f32_e32 v34, v34
	v_exp_f32_e32 v38, v38
	v_exp_f32_e32 v35, v35
	v_exp_f32_e32 v36, v36
	v_mul_f32_e32 v44, v44, v34
	v_add_f32_e32 v34, 1.0, v38
	v_add_f32_e32 v35, 1.0, v35
	v_add_f32_e32 v36, 1.0, v36
	v_mul_f32_e32 v38, 0xbfb8aa3b, v47
	v_rcp_f32_e32 v34, v34
	v_rcp_f32_e32 v35, v35
	v_rcp_f32_e32 v36, v36
	v_exp_f32_e32 v38, v38
	v_mul_f32_e32 v62, v62, v34
	v_mul_f32_e32 v46, v46, v35
	v_mul_f32_e32 v63, v63, v36
	v_add_f32_e32 v34, 1.0, v38
	v_mul_f32_e32 v35, 0xbfb8aa3b, v64
	v_mul_f32_e32 v36, 0xbfb8aa3b, v48
	v_rcp_f32_e32 v34, v34
	v_exp_f32_e32 v35, v35
	v_exp_f32_e32 v36, v36
	v_mul_f32_e32 v38, 0xbfb8aa3b, v49
	v_mul_f32_e32 v47, v47, v34
	v_add_f32_e32 v34, 1.0, v35
	v_add_f32_e32 v35, 1.0, v36
	v_mul_f32_e32 v36, 0xbfb8aa3b, v65
	v_exp_f32_e32 v36, v36
	v_exp_f32_e32 v38, v38
	v_rcp_f32_e32 v34, v34
	v_rcp_f32_e32 v35, v35
	v_add_f32_e32 v36, 1.0, v36
	v_add_f32_e32 v38, 1.0, v38
	v_rcp_f32_e32 v36, v36
	v_rcp_f32_e32 v38, v38
	v_mul_f32_e32 v64, v64, v34
	v_mul_f32_e32 v48, v48, v35
	v_permlane32_swap_b32_e32 v50, v68
	v_permlane32_swap_b32_e32 v51, v72
	v_permlane32_swap_b32_e32 v52, v69
	v_permlane32_swap_b32_e32 v53, v37
	v_lshlrev_b32_e32 v34, 1, v100
	v_mov_b32_e32 v35, v99
	v_mul_f32_e32 v65, v65, v36
	v_mul_f32_e32 v49, v49, v38
	v_permlane32_swap_b32_e32 v54, v71
	v_permlane32_swap_b32_e32 v55, v73
	v_permlane32_swap_b32_e32 v56, v40
	v_permlane32_swap_b32_e32 v57, v41
	v_lshl_add_u64 v[38:39], v[66:67], 0, v[34:35]
	v_cvt_pk_bf16_f32 v34, v50, v51
	v_cvt_pk_bf16_f32 v35, v52, v53
	v_cvt_pk_bf16_f32 v36, v68, v72
	v_cvt_pk_bf16_f32 v37, v69, v37
	v_permlane32_swap_b32_e32 v58, v42
	v_permlane32_swap_b32_e32 v59, v43
	v_permlane32_swap_b32_e32 v60, v44
	v_permlane32_swap_b32_e32 v61, v45
	ds_write_b128 v202, v[34:37]
	v_permlane32_swap_b32_e32 v62, v46
	s_nop 0
	v_cvt_pk_bf16_f32 v34, v54, v55
	v_cvt_pk_bf16_f32 v35, v56, v57
	v_cvt_pk_bf16_f32 v36, v71, v73
	v_cvt_pk_bf16_f32 v37, v40, v41
	v_permlane32_swap_b32_e32 v63, v47
	v_permlane32_swap_b32_e32 v64, v48
	v_permlane32_swap_b32_e32 v65, v49
	ds_write_b128 v202, v[34:37] offset:16
	s_nop 1
	v_cvt_pk_bf16_f32 v34, v58, v59
	v_cvt_pk_bf16_f32 v35, v60, v61
	v_cvt_pk_bf16_f32 v36, v42, v43
	v_cvt_pk_bf16_f32 v37, v44, v45
	ds_write_b128 v202, v[34:37] offset:32
	s_nop 1
	v_cvt_pk_bf16_f32 v34, v62, v63
	v_cvt_pk_bf16_f32 v35, v64, v65
	v_cvt_pk_bf16_f32 v36, v46, v47
	v_cvt_pk_bf16_f32 v37, v48, v49
	ds_write_b128 v202, v[34:37] offset:48
	v_lshl_add_u64 v[192:193], v[38:39], 0, v[206:207]
	ds_read_b128 v[176:179], v204
	ds_read_b128 v[180:183], v204 offset:144
	ds_read_b128 v[184:187], v204 offset:288
	ds_read_b128 v[188:191], v204 offset:432
	s_waitcnt lgkmcnt(3)
	global_store_dwordx4 v[192:193], v[176:179], off sc1
	s_waitcnt lgkmcnt(2)
	global_store_dwordx4 v[192:193], v[180:183], off offset:1024 sc1
	s_waitcnt lgkmcnt(1)
	global_store_dwordx4 v[192:193], v[184:187], off offset:2048 sc1
	s_waitcnt lgkmcnt(0)
	global_store_dwordx4 v[192:193], v[188:191], off offset:3072 sc1

.LBB0_324:
	s_andn2_saveexec_b64 s[14:15], s[34:35]
	s_cbranch_execz .LBB0_326
	v_mul_f32_e32 v34, 0xbfb8aa3b, v34
	v_mul_f32_e32 v35, 0xbfb8aa3b, v35
	v_exp_f32_e32 v34, v34
	v_exp_f32_e32 v35, v35
	v_mul_f32_e32 v36, 0xbfb8aa3b, v36
	v_exp_f32_e32 v36, v36
	v_add_f32_e32 v34, 1.0, v34
	v_add_f32_e32 v35, 1.0, v35
	v_rcp_f32_e32 v34, v34
	v_rcp_f32_e32 v35, v35
	v_cmp_gt_i32_e64 s[12:13], s57, v68
	v_mul_f32_e32 v50, v50, v34
	v_mul_f32_e32 v51, v51, v35
	v_add_f32_e32 v34, 1.0, v36
	v_mul_f32_e32 v35, 0xbfb8aa3b, v37
	v_mul_f32_e32 v36, 0xbfb8aa3b, v38
	v_exp_f32_e32 v35, v35
	v_exp_f32_e32 v36, v36
	v_mul_f32_e32 v37, 0xbfb8aa3b, v39
	v_rcp_f32_e32 v34, v34
	v_add_f32_e32 v35, 1.0, v35
	v_add_f32_e32 v36, 1.0, v36
	v_rcp_f32_e32 v35, v35
	v_rcp_f32_e32 v36, v36
	v_exp_f32_e32 v37, v37
	v_mul_f32_e32 v52, v52, v34
	v_mul_f32_e32 v53, v53, v35
	v_mul_f32_e32 v54, v54, v36
	v_mul_f32_e32 v35, 0xbfb8aa3b, v40
	v_mul_f32_e32 v36, 0xbfb8aa3b, v41
	v_exp_f32_e32 v35, v35
	v_exp_f32_e32 v36, v36
	v_add_f32_e32 v34, 1.0, v37
	v_mul_f32_e32 v37, 0xbfb8aa3b, v42
	v_add_f32_e32 v35, 1.0, v35
	v_add_f32_e32 v36, 1.0, v36
	v_rcp_f32_e32 v35, v35
	v_rcp_f32_e32 v36, v36
	v_rcp_f32_e32 v34, v34
	v_exp_f32_e32 v37, v37
	v_mul_f32_e32 v41, v56, v35
	v_mul_f32_e32 v42, v57, v36
	v_mul_f32_e32 v35, 0xbfb8aa3b, v43
	v_mul_f32_e32 v36, 0xbfb8aa3b, v44
	v_exp_f32_e32 v35, v35
	v_exp_f32_e32 v36, v36
	v_mul_f32_e32 v40, v55, v34
	v_add_f32_e32 v34, 1.0, v37
	v_add_f32_e32 v35, 1.0, v35
	v_add_f32_e32 v36, 1.0, v36
	v_mul_f32_e32 v37, 0xbfb8aa3b, v45
	v_rcp_f32_e32 v34, v34
	v_rcp_f32_e32 v35, v35
	v_rcp_f32_e32 v36, v36
	v_exp_f32_e32 v37, v37
	v_mul_f32_e32 v43, v58, v34
	v_mul_f32_e32 v44, v59, v35
	v_mul_f32_e32 v45, v60, v36
	v_add_f32_e32 v34, 1.0, v37
	v_mul_f32_e32 v35, 0xbfb8aa3b, v46
	v_mul_f32_e32 v36, 0xbfb8aa3b, v47
	v_rcp_f32_e32 v34, v34
	v_exp_f32_e32 v35, v35
	v_exp_f32_e32 v36, v36
	v_mul_f32_e32 v38, 0xbfb8aa3b, v49
	v_mul_f32_e32 v37, v61, v34
	v_add_f32_e32 v34, 1.0, v35
	v_add_f32_e32 v35, 1.0, v36
	v_rcp_f32_e32 v35, v35
	v_mul_f32_e32 v36, 0xbfb8aa3b, v48
	v_rcp_f32_e32 v34, v34
	v_exp_f32_e32 v36, v36
	v_exp_f32_e32 v38, v38
	v_mul_f32_e32 v47, v63, v35
	v_add_u32_e32 v35, 0xffffe020, v108
	v_lshrrev_b32_e32 v35, 12, v35
	v_add_f32_e32 v36, 1.0, v36
	v_add_f32_e32 v38, 1.0, v38
	v_mul_f32_e32 v46, v62, v34
	v_ashrrev_i32_e32 v34, 8, v66
	v_add_u32_e32 v35, 32, v35
	v_rcp_f32_e32 v36, v36
	v_rcp_f32_e32 v38, v38
	v_cndmask_b32_e64 v34, v35, v34, s[12:13]
	v_lshlrev_b32_e32 v34, 5, v34
	v_add3_u32 v34, v68, v34, 16
	v_ashrrev_i32_e32 v35, 31, v34
	v_mul_f32_e32 v48, v64, v36
	v_mul_f32_e32 v49, v65, v38
	v_permlane32_swap_b32_e32 v50, v43
	v_permlane32_swap_b32_e32 v51, v44
	v_permlane32_swap_b32_e32 v52, v45
	v_permlane32_swap_b32_e32 v53, v37
	v_lshlrev_b64 v[34:35], 10, v[34:35]
	v_permlane32_swap_b32_e32 v54, v46
	v_permlane32_swap_b32_e32 v40, v47
	v_permlane32_swap_b32_e32 v41, v48
	v_permlane32_swap_b32_e32 v42, v49
	v_lshl_add_u64 v[38:39], v[116:117], 0, v[34:35]
	v_cvt_pk_bf16_f32 v34, v50, v51
	v_cvt_pk_bf16_f32 v35, v52, v53
	v_cvt_pk_bf16_f32 v36, v43, v44
	v_cvt_pk_bf16_f32 v37, v45, v37
	ds_write_b128 v203, v[34:37]
	s_nop 1
	v_cvt_pk_bf16_f32 v34, v54, v40
	v_cvt_pk_bf16_f32 v35, v41, v42
	v_cvt_pk_bf16_f32 v36, v46, v47
	v_cvt_pk_bf16_f32 v37, v48, v49
	ds_write_b128 v203, v[34:37] offset:16
	v_lshl_add_u64 v[192:193], v[38:39], 0, v[210:211]
	ds_read_b128 v[176:179], v205
	ds_read_b128 v[180:183], v205 offset:144
	s_waitcnt lgkmcnt(1)
	global_store_dwordx4 v[192:193], v[176:179], off sc1
	s_waitcnt lgkmcnt(0)
	global_store_dwordx4 v[192:193], v[180:183], off offset:1024 sc1

.LBB0_328:
	s_and_saveexec_b64 s[10:11], s[8:9]
	s_xor_b64 s[14:15], exec, s[10:11]
	s_cbranch_execz .LBB0_380
	v_cmp_gt_i32_e64 s[8:9], s60, v108
	s_and_saveexec_b64 s[10:11], s[30:31]
	s_xor_b64 s[30:31], exec, s[10:11]
	s_cbranch_execz .LBB0_348
	v_ashrrev_i32_e32 v38, 6, v34
	v_ashrrev_i32_e32 v39, 31, v38
	v_lshl_add_u64 v[38:39], v[112:113], 0, v[38:39]
	v_lshlrev_b64 v[38:39], 6, v[38:39]
	v_and_b32_e32 v35, 63, v36
	v_lshlrev_b32_e32 v36, 1, v35
	v_mov_b32_e32 v37, v99
	v_or3_b32 v40, v38, v159, 32
	v_mov_b32_e32 v41, v39
	v_lshl_add_u64 v[36:37], s[24:25], 0, v[36:37]
	v_lshlrev_b64 v[40:41], 7, v[40:41]
	v_cvt_pk_bf16_f32 v35, v2, v3
	v_lshl_add_u64 v[40:41], v[36:37], 0, v[40:41]
	v_cvt_pk_bf16_f32 v42, v4, v5
	global_store_short v[40:41], v35, off offset:-4096
	global_store_short_d16_hi v[40:41], v35, off offset:-3968
	v_cvt_pk_bf16_f32 v43, v6, v7
	global_store_short v[40:41], v42, off offset:-3840
	global_store_short_d16_hi v[40:41], v42, off offset:-3712
	v_cvt_pk_bf16_f32 v44, v8, v9
	global_store_short v[40:41], v43, off offset:-3072
	global_store_short_d16_hi v[40:41], v43, off offset:-2944
	v_cvt_pk_bf16_f32 v45, v10, v11
	global_store_short v[40:41], v44, off offset:-2816
	global_store_short_d16_hi v[40:41], v44, off offset:-2688
	v_cvt_pk_bf16_f32 v46, v12, v13
	global_store_short v[40:41], v45, off offset:-2048
	global_store_short_d16_hi v[40:41], v45, off offset:-1920
	v_cvt_pk_bf16_f32 v47, v14, v15
	global_store_short v[40:41], v46, off offset:-1792
	global_store_short_d16_hi v[40:41], v46, off offset:-1664
	v_cvt_pk_bf16_f32 v48, v16, v17
	global_store_short v[40:41], v47, off offset:-1024
	global_store_short_d16_hi v[40:41], v47, off offset:-896
	v_cvt_pk_bf16_f32 v49, v18, v19
	global_store_short v[40:41], v48, off offset:-768
	global_store_short_d16_hi v[40:41], v48, off offset:-640
	v_cvt_pk_bf16_f32 v50, v20, v21
	global_store_short v[40:41], v49, off
	global_store_short_d16_hi v[40:41], v49, off offset:128
	v_cvt_pk_bf16_f32 v51, v22, v23
	global_store_short v[40:41], v50, off offset:256
	global_store_short_d16_hi v[40:41], v50, off offset:384
	v_cvt_pk_bf16_f32 v52, v24, v25
	global_store_short v[40:41], v51, off offset:1024
	global_store_short_d16_hi v[40:41], v51, off offset:1152
	v_cvt_pk_bf16_f32 v53, v26, v27
	global_store_short v[40:41], v52, off offset:1280
	global_store_short_d16_hi v[40:41], v52, off offset:1408
	v_cvt_pk_bf16_f32 v54, v28, v29
	global_store_short v[40:41], v53, off offset:2048
	global_store_short_d16_hi v[40:41], v53, off offset:2176
	v_cvt_pk_bf16_f32 v55, v30, v31
	global_store_short v[40:41], v54, off offset:2304
	global_store_short_d16_hi v[40:41], v54, off offset:2432
	v_cvt_pk_bf16_f32 v56, v32, v33
	global_store_short v[40:41], v55, off offset:3072
	global_store_short_d16_hi v[40:41], v55, off offset:3200
	global_store_short v[40:41], v56, off offset:3328
	global_store_short_d16_hi v[40:41], v56, off offset:3456
	s_and_saveexec_b64 s[34:35], s[8:9]
	s_cbranch_execz .LBB0_347
	v_permlane32_swap_b32_e32 v2, v18
	v_permlane32_swap_b32_e32 v3, v19
	v_permlane32_swap_b32_e32 v4, v20
	v_permlane32_swap_b32_e32 v5, v21
	v_ashrrev_i32_e32 v35, 31, v34
	v_permlane32_swap_b32_e32 v6, v22
	v_permlane32_swap_b32_e32 v7, v23
	v_permlane32_swap_b32_e32 v8, v24
	v_permlane32_swap_b32_e32 v9, v25
	v_permlane32_swap_b32_e32 v10, v26
	v_permlane32_swap_b32_e32 v11, v27
	v_permlane32_swap_b32_e32 v12, v28
	v_permlane32_swap_b32_e32 v13, v29
	v_permlane32_swap_b32_e32 v14, v30
	v_permlane32_swap_b32_e32 v15, v31
	v_permlane32_swap_b32_e32 v16, v32
	v_permlane32_swap_b32_e32 v17, v33
	ds_write_b128 v156, v[2:5]
	ds_write_b128 v156, v[18:21] offset:16
	ds_write_b128 v156, v[6:9] offset:32
	ds_write_b128 v156, v[22:25] offset:48
	ds_write_b128 v156, v[10:13] offset:64
	ds_write_b128 v156, v[26:29] offset:80
	ds_write_b128 v156, v[14:17] offset:96
	ds_write_b128 v156, v[30:33] offset:112
	v_lshlrev_b64 v[2:3], 11, v[34:35]
	v_lshl_add_u64 v[2:3], s[26:27], 0, v[2:3]
	v_lshl_add_u64 v[2:3], v[98:99], 2, v[2:3]
	v_lshlrev_b32_e32 v98, 2, v155
	v_or_b32_e32 v4, v34, v154
	v_lshl_add_u64 v[2:3], v[2:3], 0, v[98:99]
	v_cmp_gt_i32_e64 s[10:11], s57, v4
	s_and_saveexec_b64 s[36:37], s[10:11]
	s_cbranch_execz .LBB0_333
	v_add_u32_e32 v4, v139, v152
	ds_read_b128 v[4:7], v4
	v_lshlrev_b32_e32 v98, 2, v153
	v_lshl_add_u64 v[8:9], v[2:3], 0, v[98:99]
	s_waitcnt lgkmcnt(0)
	global_store_dwordx4 v[8:9], v[4:7], off sc1
.LBB0_333:
	s_or_b64 exec, exec, s[36:37]
	s_nop 0
	v_or_b32_e32 v4, v34, v151
	v_cmp_gt_i32_e64 s[10:11], s57, v4
	s_and_saveexec_b64 s[36:37], s[10:11]
	s_cbranch_execz .LBB0_335
	v_add_u32_e32 v4, v139, v149
	ds_read_b128 v[4:7], v4
	v_lshlrev_b32_e32 v98, 2, v150
	v_lshl_add_u64 v[8:9], v[2:3], 0, v[98:99]
	s_waitcnt lgkmcnt(0)
	global_store_dwordx4 v[8:9], v[4:7], off sc1
.LBB0_335:
	s_or_b64 exec, exec, s[36:37]
	s_nop 0
	v_or_b32_e32 v4, v34, v148
	v_cmp_gt_i32_e64 s[10:11], s57, v4
	s_and_saveexec_b64 s[36:37], s[10:11]
	s_cbranch_execz .LBB0_337
	v_add_u32_e32 v4, v139, v141
	ds_read_b128 v[4:7], v4
	v_lshlrev_b32_e32 v98, 2, v147
	v_lshl_add_u64 v[8:9], v[2:3], 0, v[98:99]
	s_waitcnt lgkmcnt(0)
	global_store_dwordx4 v[8:9], v[4:7], off sc1
.LBB0_337:
	s_or_b64 exec, exec, s[36:37]
	s_nop 0
	v_or_b32_e32 v4, v34, v146
	v_cmp_gt_i32_e64 s[10:11], s57, v4
	s_and_saveexec_b64 s[36:37], s[10:11]
	s_cbranch_execz .LBB0_339
	v_add_u32_e32 v4, v139, v141
	ds_read_b128 v[4:7], v4 offset:1088
	v_lshlrev_b32_e32 v98, 2, v145
	v_lshl_add_u64 v[8:9], v[2:3], 0, v[98:99]
	s_waitcnt lgkmcnt(0)
	global_store_dwordx4 v[8:9], v[4:7], off sc1
.LBB0_339:
	s_or_b64 exec, exec, s[36:37]
	s_nop 0
	v_or_b32_e32 v4, v34, v144
	v_cmp_gt_i32_e64 s[10:11], s57, v4
	s_and_saveexec_b64 s[36:37], s[10:11]
	s_cbranch_execz .LBB0_341
	v_add_u32_e32 v4, v139, v141
	ds_read_b128 v[4:7], v4 offset:2176
	v_lshlrev_b32_e32 v98, 2, v143
	v_lshl_add_u64 v[8:9], v[2:3], 0, v[98:99]
	s_waitcnt lgkmcnt(0)
	global_store_dwordx4 v[8:9], v[4:7], off sc1
.LBB0_341:
	s_or_b64 exec, exec, s[36:37]
	s_nop 0
	v_or_b32_e32 v4, v34, v142
	v_cmp_gt_i32_e64 s[10:11], s57, v4
	s_and_saveexec_b64 s[36:37], s[10:11]
	s_cbranch_execz .LBB0_343
	v_add_u32_e32 v4, v139, v141
	ds_read_b128 v[4:7], v4 offset:3264
	v_lshlrev_b32_e32 v98, 2, v140
	v_lshl_add_u64 v[8:9], v[2:3], 0, v[98:99]
	s_waitcnt lgkmcnt(0)
	global_store_dwordx4 v[8:9], v[4:7], off sc1
.LBB0_343:
	s_or_b64 exec, exec, s[36:37]
	s_nop 0
	v_or_b32_e32 v4, v34, v138
	v_cmp_gt_i32_e64 s[10:11], s57, v4
	s_and_saveexec_b64 s[36:37], s[10:11]
	s_cbranch_execz .LBB0_345
	v_add_u32_e32 v4, v139, v141
	ds_read_b128 v[4:7], v4 offset:4352
	v_lshlrev_b32_e32 v98, 2, v137
	v_lshl_add_u64 v[8:9], v[2:3], 0, v[98:99]
	s_waitcnt lgkmcnt(0)
	global_store_dwordx4 v[8:9], v[4:7], off sc1
.LBB0_345:
	s_or_b64 exec, exec, s[36:37]
	s_nop 0
	v_or_b32_e32 v4, v34, v136
	v_cmp_gt_i32_e64 s[10:11], s57, v4
	s_and_b64 exec, exec, s[10:11]
	s_cbranch_execz .LBB0_347
	v_add_u32_e32 v4, v139, v141
	ds_read_b128 v[4:7], v4 offset:5440
	v_lshlrev_b32_e32 v98, 2, v135
	v_lshl_add_u64 v[2:3], v[2:3], 0, v[98:99]
	s_waitcnt lgkmcnt(0)
	global_store_dwordx4 v[2:3], v[4:7], off sc1

.LBB0_361:
	s_or_b64 exec, exec, s[6:7]
	v_pk_mul_f32 v[6:7], v[104:105], v[6:7]
	v_pk_mul_f32 v[8:9], v[104:105], v[8:9]
	v_pk_mul_f32 v[2:3], v[104:105], v[2:3]
	v_cvt_pk_bf16_f32 v6, v6, v7
	v_cvt_pk_bf16_f32 v7, v8, v9
	v_cvt_pk_bf16_f32 v8, v2, v3
	v_pk_mul_f32 v[2:3], v[104:105], v[4:5]
	s_and_b64 s[4:5], s[4:5], s[8:9]
	v_cvt_pk_bf16_f32 v9, v2, v3
	ds_write_b128 v202, v[6:9] offset:48
	ds_read_b128 v[176:179], v204
	ds_read_b128 v[180:183], v204 offset:144
	ds_read_b128 v[184:187], v204 offset:288
	ds_read_b128 v[188:191], v204 offset:432
	s_cmp_lg_u64 s[98:99], 0
	s_cbranch_scc0 .Lg1co_k6
	v_lshl_add_u64 v[192:193], v[40:41], 0, v[206:207]
	s_waitcnt lgkmcnt(3)
	global_store_dwordx4 v[192:193], v[176:179], off sc1
	s_waitcnt lgkmcnt(2)
	global_store_dwordx4 v[192:193], v[180:183], off offset:1024 sc1
	s_waitcnt lgkmcnt(1)
	global_store_dwordx4 v[192:193], v[184:187], off offset:2048 sc1
	s_waitcnt lgkmcnt(0)
	global_store_dwordx4 v[192:193], v[188:191], off offset:3072 sc1
	s_branch .Lg1co_e6
.Lg1co_k6:
	v_lshl_add_u64 v[192:193], v[40:41], 0, v[208:209]
	s_waitcnt lgkmcnt(3)
	global_store_dwordx4 v[192:193], v[176:179], off sc1
	s_waitcnt lgkmcnt(2)
	global_store_dwordx4 v[192:193], v[180:183], off offset:128 sc1
	s_waitcnt lgkmcnt(1)
	global_store_dwordx4 v[192:193], v[184:187], off offset:256 sc1
	s_waitcnt lgkmcnt(0)
	global_store_dwordx4 v[192:193], v[188:191], off offset:384 sc1
.Lg1co_e6:
	s_and_saveexec_b64 s[6:7], s[4:5]
	s_cbranch_execz .LBB0_378
	v_ashrrev_i32_e32 v35, 31, v34
	v_lshlrev_b64 v[2:3], 11, v[34:35]
	v_lshl_add_u64 v[2:3], s[28:29], 0, v[2:3]
	v_lshl_add_u64 v[2:3], v[102:103], 2, v[2:3]
	v_lshlrev_b32_e32 v98, 2, v155
	v_or_b32_e32 v4, v34, v154
	v_lshl_add_u64 v[2:3], v[2:3], 0, v[98:99]
	v_cmp_gt_i32_e64 s[4:5], s57, v4
	s_and_saveexec_b64 s[8:9], s[4:5]
	s_cbranch_execz .LBB0_364
	v_add_u32_e32 v4, v139, v152
	ds_read_b128 v[4:7], v4
	v_lshlrev_b32_e32 v98, 2, v153
	v_lshl_add_u64 v[8:9], v[2:3], 0, v[98:99]
	s_waitcnt lgkmcnt(0)
	global_store_dwordx4 v[8:9], v[4:7], off sc1
.LBB0_364:
	s_or_b64 exec, exec, s[8:9]
	s_nop 0
	v_or_b32_e32 v4, v34, v151
	v_cmp_gt_i32_e64 s[4:5], s57, v4
	s_and_saveexec_b64 s[8:9], s[4:5]
	s_cbranch_execz .LBB0_366
	v_add_u32_e32 v4, v139, v149
	ds_read_b128 v[4:7], v4
	v_lshlrev_b32_e32 v98, 2, v150
	v_lshl_add_u64 v[8:9], v[2:3], 0, v[98:99]
	s_waitcnt lgkmcnt(0)
	global_store_dwordx4 v[8:9], v[4:7], off sc1
.LBB0_366:
	s_or_b64 exec, exec, s[8:9]
	s_nop 0
	v_or_b32_e32 v4, v34, v148
	v_cmp_gt_i32_e64 s[4:5], s57, v4
	v_add_u32_e32 v4, v139, v141
	s_and_saveexec_b64 s[8:9], s[4:5]
	s_cbranch_execz .LBB0_368
	ds_read_b128 v[6:9], v4
	v_lshlrev_b32_e32 v98, 2, v147
	v_lshl_add_u64 v[10:11], v[2:3], 0, v[98:99]
	s_waitcnt lgkmcnt(0)
	global_store_dwordx4 v[10:11], v[6:9], off sc1
.LBB0_368:
	s_or_b64 exec, exec, s[8:9]
	v_or_b32_e32 v5, v34, v146
	v_cmp_gt_i32_e64 s[4:5], s57, v5
	s_and_saveexec_b64 s[8:9], s[4:5]
	s_cbranch_execz .LBB0_370
	ds_read_b128 v[6:9], v4 offset:1088
	v_lshlrev_b32_e32 v98, 2, v145
	v_lshl_add_u64 v[10:11], v[2:3], 0, v[98:99]
	s_waitcnt lgkmcnt(0)
	global_store_dwordx4 v[10:11], v[6:9], off sc1
.LBB0_370:
	s_or_b64 exec, exec, s[8:9]
	v_or_b32_e32 v5, v34, v144
	v_cmp_gt_i32_e64 s[4:5], s57, v5
	s_and_saveexec_b64 s[8:9], s[4:5]
	s_cbranch_execz .LBB0_372
	ds_read_b128 v[6:9], v4 offset:2176
	v_lshlrev_b32_e32 v98, 2, v143
	v_lshl_add_u64 v[10:11], v[2:3], 0, v[98:99]
	s_waitcnt lgkmcnt(0)
	global_store_dwordx4 v[10:11], v[6:9], off sc1
.LBB0_372:
	s_or_b64 exec, exec, s[8:9]
	v_or_b32_e32 v5, v34, v142
	v_cmp_gt_i32_e64 s[4:5], s57, v5
	s_and_saveexec_b64 s[8:9], s[4:5]
	s_cbranch_execz .LBB0_374
	ds_read_b128 v[6:9], v4 offset:3264
	v_lshlrev_b32_e32 v98, 2, v140
	v_lshl_add_u64 v[10:11], v[2:3], 0, v[98:99]
	s_waitcnt lgkmcnt(0)
	global_store_dwordx4 v[10:11], v[6:9], off sc1
.LBB0_374:
	s_or_b64 exec, exec, s[8:9]
	v_or_b32_e32 v5, v34, v138
	v_cmp_gt_i32_e64 s[4:5], s57, v5
	s_and_saveexec_b64 s[8:9], s[4:5]
	s_cbranch_execz .LBB0_376
	ds_read_b128 v[6:9], v4 offset:4352
	v_lshlrev_b32_e32 v98, 2, v137
	v_lshl_add_u64 v[10:11], v[2:3], 0, v[98:99]
	s_waitcnt lgkmcnt(0)
	global_store_dwordx4 v[10:11], v[6:9], off sc1
.LBB0_376:
	s_or_b64 exec, exec, s[8:9]
	v_or_b32_e32 v5, v34, v136
	v_cmp_gt_i32_e64 s[4:5], s57, v5
	s_and_b64 exec, exec, s[4:5]
	s_cbranch_execz .LBB0_378
	ds_read_b128 v[4:7], v4 offset:5440
	v_lshlrev_b32_e32 v98, 2, v135
	v_lshl_add_u64 v[2:3], v[2:3], 0, v[98:99]
	s_waitcnt lgkmcnt(0)
	global_store_dwordx4 v[2:3], v[4:7], off sc1

.LBB0_380:
	s_andn2_saveexec_b64 s[4:5], s[14:15]
	s_cbranch_execz .LBB0_382
	v_ashrrev_i32_e32 v37, 31, v36
	v_lshlrev_b64 v[34:35], 10, v[36:37]
	v_mul_f32_e32 v37, 0xbfb8aa3b, v18
	v_mul_f32_e32 v38, 0xbfb8aa3b, v3
	v_exp_f32_e32 v37, v37
	v_exp_f32_e32 v38, v38
	v_mul_f32_e32 v36, 0xbfb8aa3b, v2
	v_exp_f32_e32 v36, v36
	v_add_f32_e32 v37, 1.0, v37
	v_add_f32_e32 v38, 1.0, v38
	v_rcp_f32_e32 v37, v37
	v_rcp_f32_e32 v38, v38
	v_add_f32_e32 v36, 1.0, v36
	v_mul_f32_e32 v39, 0xbfb8aa3b, v19
	v_mul_f32_e32 v18, v18, v37
	v_mul_f32_e32 v3, v3, v38
	v_mul_f32_e32 v37, 0xbfb8aa3b, v4
	v_mul_f32_e32 v38, 0xbfb8aa3b, v20
	v_exp_f32_e32 v37, v37
	v_exp_f32_e32 v38, v38
	v_rcp_f32_e32 v36, v36
	v_exp_f32_e32 v39, v39
	v_add_f32_e32 v37, 1.0, v37
	v_add_f32_e32 v38, 1.0, v38
	v_rcp_f32_e32 v37, v37
	v_rcp_f32_e32 v38, v38
	v_mul_f32_e32 v2, v2, v36
	v_add_f32_e32 v36, 1.0, v39
	v_mul_f32_e32 v39, 0xbfb8aa3b, v5
	v_mul_f32_e32 v4, v4, v37
	v_mul_f32_e32 v20, v20, v38
	v_mul_f32_e32 v37, 0xbfb8aa3b, v21
	v_mul_f32_e32 v38, 0xbfb8aa3b, v6
	v_rcp_f32_e32 v36, v36
	v_exp_f32_e32 v39, v39
	v_exp_f32_e32 v37, v37
	v_exp_f32_e32 v38, v38
	v_mul_f32_e32 v19, v19, v36
	v_add_f32_e32 v36, 1.0, v39
	v_add_f32_e32 v37, 1.0, v37
	v_add_f32_e32 v38, 1.0, v38
	v_rcp_f32_e32 v36, v36
	v_rcp_f32_e32 v37, v37
	v_rcp_f32_e32 v38, v38
	v_mul_f32_e32 v39, 0xbfb8aa3b, v22
	v_mul_f32_e32 v5, v5, v36
	v_mul_f32_e32 v21, v21, v37
	v_mul_f32_e32 v36, v6, v38
	v_mul_f32_e32 v37, 0xbfb8aa3b, v7
	v_mul_f32_e32 v38, 0xbfb8aa3b, v23
	v_exp_f32_e32 v37, v37
	v_exp_f32_e32 v38, v38
	v_exp_f32_e32 v39, v39
	v_lshl_add_u64 v[34:35], v[114:115], 0, v[34:35]
	v_add_f32_e32 v37, 1.0, v37
	v_add_f32_e32 v38, 1.0, v38
	v_rcp_f32_e32 v37, v37
	v_rcp_f32_e32 v38, v38
	v_add_f32_e32 v6, 1.0, v39
	v_mul_f32_e32 v39, 0xbfb8aa3b, v8
	v_mul_f32_e32 v37, v7, v37
	v_mul_f32_e32 v23, v23, v38
	v_mul_f32_e32 v7, 0xbfb8aa3b, v24
	v_mul_f32_e32 v38, 0xbfb8aa3b, v9
	v_exp_f32_e32 v7, v7
	v_exp_f32_e32 v38, v38
	v_rcp_f32_e32 v6, v6
	v_exp_f32_e32 v39, v39
	v_add_f32_e32 v7, 1.0, v7
	v_add_f32_e32 v38, 1.0, v38
	v_rcp_f32_e32 v7, v7
	v_rcp_f32_e32 v38, v38
	v_mul_f32_e32 v22, v22, v6
	v_add_f32_e32 v6, 1.0, v39
	v_mul_f32_e32 v24, v24, v7
	v_mul_f32_e32 v9, v9, v38
	v_mul_f32_e32 v7, 0xbfb8aa3b, v10
	v_mul_f32_e32 v38, 0xbfb8aa3b, v26
	v_exp_f32_e32 v7, v7
	v_exp_f32_e32 v38, v38
	v_mul_f32_e32 v39, 0xbfb8aa3b, v25
	v_rcp_f32_e32 v6, v6
	v_add_f32_e32 v7, 1.0, v7
	v_add_f32_e32 v38, 1.0, v38
	v_rcp_f32_e32 v7, v7
	v_rcp_f32_e32 v38, v38
	v_exp_f32_e32 v39, v39
	v_mul_f32_e32 v8, v8, v6
	v_mul_f32_e32 v10, v10, v7
	v_mul_f32_e32 v26, v26, v38
	v_mul_f32_e32 v7, 0xbfb8aa3b, v27
	v_mul_f32_e32 v38, 0xbfb8aa3b, v12
	v_exp_f32_e32 v7, v7
	v_exp_f32_e32 v38, v38
	v_add_f32_e32 v6, 1.0, v39
	v_mul_f32_e32 v39, 0xbfb8aa3b, v11
	v_add_f32_e32 v7, 1.0, v7
	v_add_f32_e32 v38, 1.0, v38
	v_rcp_f32_e32 v7, v7
	v_rcp_f32_e32 v38, v38
	v_rcp_f32_e32 v6, v6
	v_exp_f32_e32 v39, v39
	v_mul_f32_e32 v27, v27, v7
	v_mul_f32_e32 v12, v12, v38
	v_mul_f32_e32 v7, 0xbfb8aa3b, v13
	v_mul_f32_e32 v38, 0xbfb8aa3b, v29
	v_exp_f32_e32 v7, v7
	v_exp_f32_e32 v38, v38
	v_mul_f32_e32 v25, v25, v6
	v_add_f32_e32 v6, 1.0, v39
	v_mul_f32_e32 v39, 0xbfb8aa3b, v28
	v_add_f32_e32 v7, 1.0, v7
	v_add_f32_e32 v38, 1.0, v38
	v_rcp_f32_e32 v6, v6
	v_exp_f32_e32 v39, v39
	v_rcp_f32_e32 v7, v7
	v_rcp_f32_e32 v38, v38
	v_mul_f32_e32 v11, v11, v6
	v_add_f32_e32 v6, 1.0, v39
	v_mul_f32_e32 v39, 0xbfb8aa3b, v14
	v_mul_f32_e32 v13, v13, v7
	v_mul_f32_e32 v29, v29, v38
	v_mul_f32_e32 v7, 0xbfb8aa3b, v30
	v_mul_f32_e32 v38, 0xbfb8aa3b, v15
	v_rcp_f32_e32 v6, v6
	v_exp_f32_e32 v39, v39
	v_exp_f32_e32 v7, v7
	v_exp_f32_e32 v38, v38
	v_mul_f32_e32 v28, v28, v6
	v_add_f32_e32 v6, 1.0, v39
	v_add_f32_e32 v7, 1.0, v7
	v_add_f32_e32 v38, 1.0, v38
	v_mul_f32_e32 v39, 0xbfb8aa3b, v31
	v_rcp_f32_e32 v6, v6
	v_rcp_f32_e32 v7, v7
	v_rcp_f32_e32 v38, v38
	v_exp_f32_e32 v39, v39
	v_mul_f32_e32 v14, v14, v6
	v_mul_f32_e32 v30, v30, v7
	v_mul_f32_e32 v15, v15, v38
	v_add_f32_e32 v6, 1.0, v39
	v_mul_f32_e32 v7, 0xbfb8aa3b, v16
	v_mul_f32_e32 v38, 0xbfb8aa3b, v32
	v_rcp_f32_e32 v6, v6
	v_exp_f32_e32 v7, v7
	v_exp_f32_e32 v38, v38
	v_mul_f32_e32 v39, 0xbfb8aa3b, v33
	v_mul_f32_e32 v31, v31, v6
	v_add_f32_e32 v6, 1.0, v7
	v_add_f32_e32 v7, 1.0, v38
	v_mul_f32_e32 v38, 0xbfb8aa3b, v17
	v_exp_f32_e32 v38, v38
	v_exp_f32_e32 v39, v39
	v_rcp_f32_e32 v6, v6
	v_rcp_f32_e32 v7, v7
	v_add_f32_e32 v38, 1.0, v38
	v_add_f32_e32 v39, 1.0, v39
	v_rcp_f32_e32 v38, v38
	v_rcp_f32_e32 v39, v39
	v_cndmask_b32_e32 v98, v133, v134, vcc
	v_lshl_add_u64 v[34:35], v[34:35], 0, v[98:99]
	v_permlane32_swap_b32_e32 v2, v18
	v_permlane32_swap_b32_e32 v3, v19
	v_permlane32_swap_b32_e32 v4, v20
	v_permlane32_swap_b32_e32 v5, v21
	v_lshlrev_b32_e32 v98, 1, v100
	v_mul_f32_e32 v16, v16, v6
	v_mul_f32_e32 v32, v32, v7
	v_permlane32_swap_b32_e32 v36, v22
	v_permlane32_swap_b32_e32 v37, v23
	v_permlane32_swap_b32_e32 v8, v24
	v_permlane32_swap_b32_e32 v9, v25
	v_lshl_add_u64 v[6:7], v[34:35], 0, v[98:99]
	v_cvt_pk_bf16_f32 v2, v2, v3
	v_cvt_pk_bf16_f32 v3, v4, v5
	v_cvt_pk_bf16_f32 v4, v18, v19
	v_cvt_pk_bf16_f32 v5, v20, v21
	v_mul_f32_e32 v17, v17, v38
	v_mul_f32_e32 v33, v33, v39
	v_permlane32_swap_b32_e32 v10, v26
	v_permlane32_swap_b32_e32 v11, v27
	v_permlane32_swap_b32_e32 v12, v28
	v_permlane32_swap_b32_e32 v13, v29
	ds_write_b128 v202, v[2:5]
	v_permlane32_swap_b32_e32 v14, v30
	s_nop 0
	v_cvt_pk_bf16_f32 v2, v36, v37
	v_cvt_pk_bf16_f32 v3, v8, v9
	v_cvt_pk_bf16_f32 v4, v22, v23
	v_cvt_pk_bf16_f32 v5, v24, v25
	v_permlane32_swap_b32_e32 v15, v31
	v_permlane32_swap_b32_e32 v16, v32
	v_permlane32_swap_b32_e32 v17, v33
	ds_write_b128 v202, v[2:5] offset:16
	s_nop 1
	v_cvt_pk_bf16_f32 v2, v10, v11
	v_cvt_pk_bf16_f32 v3, v12, v13
	v_cvt_pk_bf16_f32 v4, v26, v27
	v_cvt_pk_bf16_f32 v5, v28, v29
	ds_write_b128 v202, v[2:5] offset:32
	s_nop 1
	v_cvt_pk_bf16_f32 v2, v14, v15
	v_cvt_pk_bf16_f32 v3, v16, v17
	v_cvt_pk_bf16_f32 v4, v30, v31
	v_cvt_pk_bf16_f32 v5, v32, v33
	ds_write_b128 v202, v[2:5] offset:48
	v_lshl_add_u64 v[192:193], v[6:7], 0, v[206:207]
	ds_read_b128 v[176:179], v204
	ds_read_b128 v[180:183], v204 offset:144
	ds_read_b128 v[184:187], v204 offset:288
	ds_read_b128 v[188:191], v204 offset:432
	s_waitcnt lgkmcnt(3)
	global_store_dwordx4 v[192:193], v[176:179], off sc1
	s_waitcnt lgkmcnt(2)
	global_store_dwordx4 v[192:193], v[180:183], off offset:1024 sc1
	s_waitcnt lgkmcnt(1)
	global_store_dwordx4 v[192:193], v[184:187], off offset:2048 sc1
	s_waitcnt lgkmcnt(0)
	global_store_dwordx4 v[192:193], v[188:191], off offset:3072 sc1

.LBB0_383:
	v_mul_f32_e32 v18, 0xbfb8aa3b, v18
	v_mul_f32_e32 v19, 0xbfb8aa3b, v19
	v_exp_f32_e32 v18, v18
	v_exp_f32_e32 v19, v19
	v_mul_f32_e32 v20, 0xbfb8aa3b, v20
	v_exp_f32_e32 v20, v20
	v_add_f32_e32 v18, 1.0, v18
	v_add_f32_e32 v19, 1.0, v19
	v_rcp_f32_e32 v18, v18
	v_rcp_f32_e32 v19, v19
	v_cmp_gt_i32_e32 vcc, s57, v36
	v_mul_f32_e32 v18, v2, v18
	v_mul_f32_e32 v19, v3, v19
	v_add_f32_e32 v2, 1.0, v20
	v_mul_f32_e32 v3, 0xbfb8aa3b, v21
	v_mul_f32_e32 v20, 0xbfb8aa3b, v22
	v_exp_f32_e32 v3, v3
	v_exp_f32_e32 v20, v20
	v_mul_f32_e32 v21, 0xbfb8aa3b, v23
	v_rcp_f32_e32 v2, v2
	v_add_f32_e32 v3, 1.0, v3
	v_add_f32_e32 v20, 1.0, v20
	v_rcp_f32_e32 v3, v3
	v_rcp_f32_e32 v20, v20
	v_exp_f32_e32 v21, v21
	v_mul_f32_e32 v4, v4, v2
	v_mul_f32_e32 v5, v5, v3
	v_mul_f32_e32 v20, v6, v20
	v_mul_f32_e32 v3, 0xbfb8aa3b, v24
	v_mul_f32_e32 v6, 0xbfb8aa3b, v25
	v_exp_f32_e32 v3, v3
	v_exp_f32_e32 v6, v6
	v_add_f32_e32 v2, 1.0, v21
	v_mul_f32_e32 v21, 0xbfb8aa3b, v26
	v_add_f32_e32 v3, 1.0, v3
	v_add_f32_e32 v6, 1.0, v6
	v_rcp_f32_e32 v3, v3
	v_rcp_f32_e32 v6, v6
	v_rcp_f32_e32 v2, v2
	v_exp_f32_e32 v21, v21
	v_mul_f32_e32 v8, v8, v3
	v_mul_f32_e32 v9, v9, v6
	v_mul_f32_e32 v3, 0xbfb8aa3b, v27
	v_mul_f32_e32 v6, 0xbfb8aa3b, v28
	v_exp_f32_e32 v3, v3
	v_exp_f32_e32 v6, v6
	v_mul_f32_e32 v22, v7, v2
	v_add_f32_e32 v2, 1.0, v21
	v_add_f32_e32 v3, 1.0, v3
	v_add_f32_e32 v6, 1.0, v6
	v_mul_f32_e32 v7, 0xbfb8aa3b, v29
	v_rcp_f32_e32 v2, v2
	v_rcp_f32_e32 v3, v3
	v_rcp_f32_e32 v6, v6
	v_exp_f32_e32 v7, v7
	v_mul_f32_e32 v10, v10, v2
	v_mul_f32_e32 v11, v11, v3
	v_mul_f32_e32 v12, v12, v6
	v_add_f32_e32 v2, 1.0, v7
	v_mul_f32_e32 v3, 0xbfb8aa3b, v30
	v_mul_f32_e32 v6, 0xbfb8aa3b, v31
	v_rcp_f32_e32 v2, v2
	v_exp_f32_e32 v3, v3
	v_exp_f32_e32 v6, v6
	v_mul_f32_e32 v7, 0xbfb8aa3b, v33
	v_mul_f32_e32 v13, v13, v2
	v_add_f32_e32 v2, 1.0, v3
	v_add_f32_e32 v3, 1.0, v6
	v_rcp_f32_e32 v3, v3
	v_mul_f32_e32 v6, 0xbfb8aa3b, v32
	v_rcp_f32_e32 v2, v2
	v_exp_f32_e32 v6, v6
	v_exp_f32_e32 v7, v7
	v_mul_f32_e32 v15, v15, v3
	v_add_u32_e32 v3, 0xffffe040, v108
	v_lshrrev_b32_e32 v3, 12, v3
	v_add_f32_e32 v6, 1.0, v6
	v_add_f32_e32 v7, 1.0, v7
	v_mul_f32_e32 v14, v14, v2
	v_ashrrev_i32_e32 v2, 8, v34
	v_add_u32_e32 v3, 32, v3
	v_rcp_f32_e32 v6, v6
	v_rcp_f32_e32 v7, v7
	v_cndmask_b32_e32 v2, v3, v2, vcc
	v_lshlrev_b32_e32 v2, 5, v2
	v_add3_u32 v2, v36, v2, 16
	v_ashrrev_i32_e32 v3, 31, v2
	v_mul_f32_e32 v16, v16, v6
	v_mul_f32_e32 v17, v17, v7
	v_permlane32_swap_b32_e32 v18, v10
	v_permlane32_swap_b32_e32 v19, v11
	v_permlane32_swap_b32_e32 v4, v12
	v_permlane32_swap_b32_e32 v5, v13
	v_lshlrev_b64 v[2:3], 10, v[2:3]
	v_permlane32_swap_b32_e32 v20, v14
	v_permlane32_swap_b32_e32 v22, v15
	v_permlane32_swap_b32_e32 v8, v16
	v_permlane32_swap_b32_e32 v9, v17
	v_lshl_add_u64 v[6:7], v[116:117], 0, v[2:3]
	v_cvt_pk_bf16_f32 v2, v18, v19
	v_cvt_pk_bf16_f32 v3, v4, v5
	v_cvt_pk_bf16_f32 v4, v10, v11
	v_cvt_pk_bf16_f32 v5, v12, v13
	ds_write_b128 v203, v[2:5]
	s_nop 1
	v_cvt_pk_bf16_f32 v2, v20, v22
	v_cvt_pk_bf16_f32 v3, v8, v9
	v_cvt_pk_bf16_f32 v4, v14, v15
	v_cvt_pk_bf16_f32 v5, v16, v17
	ds_write_b128 v203, v[2:5] offset:16
	v_lshl_add_u64 v[192:193], v[6:7], 0, v[210:211]
	ds_read_b128 v[176:179], v205
	ds_read_b128 v[180:183], v205 offset:144
	s_waitcnt lgkmcnt(1)
	global_store_dwordx4 v[192:193], v[176:179], off sc1
	s_waitcnt lgkmcnt(0)
	global_store_dwordx4 v[192:193], v[180:183], off offset:1024 sc1
	s_branch .LBB0_204
